# leading-half alignment barrier moved after the epilogue's load issue (P3, P4, P6)
# speedup vs baseline: 1.0045x; 1.0045x over previous
; #define PG8_BAR __builtin_amdgcn_s_barrier()
; __device__ __forceinline__ unsigned pk4_fp8g(float a, float b, float c, float d) { int r = __builtin_amdgcn_cvt_pk_fp8_f32(a, b, 0, false); r = __builtin_amdgcn_cvt_pk_fp8_f32(c, d, r, true); return (unsigned)r; }
; #define G2B(bw, sh) (fmaxf((float)(((bw) >> (sh)) & 0xffu), 0.5f) * (1.f / 2040.f))
; template <class Epi, class Sched, bool ALIGN_EPI = false, bool SP2 = false, bool FP8 = false>
; __device__ __forceinline__ void gemm_phase(PG8_LAS unsigned char* lds, const Gemm g, const Sched& S, const Epi& E) {
;     ...
;         if constexpr (ALIGN_EPI) { if (wr == 0) PG8_BAR; }
;     __device__ __forceinline__ void operator()(const f32x4 (&acc)[2][2][4][2], const Unit& u, int wr, int wc, int fr, int fq) const {
;         asm volatile("" : "+v"(fr), "+v"(fq));
;         const int row0 = u.pm * BM + wr * 64 + fr, col0 = u.pn * BM + wc * 32 + 8 * fq;
; #pragma unroll
;         for (int ai = 0; ai < 2; ++ai)
; #pragma unroll
;             for (int m = 0; m < 4; ++m) { const size_t r = (size_t)(row0 + ai * HALF + m * 16);
; #pragma unroll
;                 for (int bj = 0; bj < 2; ++bj) {
;                     const u32x2g b = *(const u32x2g*)(Gt + r * GC + DM + col0 + bj * HALF);
;                     f32x4 v0 = acc[ai][bj][m][0], v1 = acc[ai][bj][m][1];
;     ...
;                     v0[0] *= G2B(b.x, 0); v0[1] *= G2B(b.x, 8); v0[2] *= G2B(b.x, 16); v0[3] *= G2B(b.x, 24);
;                     v1[0] *= G2B(b.y, 0); v1[1] *= G2B(b.y, 8); v1[2] *= G2B(b.y, 16); v1[3] *= G2B(b.y, 24);
;     ...
;                     u32x2g w; w.x = pk4_fp8g(v0[0], v0[1], v0[2], v0[3]); w.y = pk4_fp8g(v1[0], v1[1], v1[2], v1[3]);
;                     *(u32x2g*)((unsigned char*)O + r * DM + col0 + bj * HALF) = w; }
.LBB0_310:
	v_mov_b32_e32 v128, v151
	v_mov_b32_e32 v130, v150
	v_mov_b32_e32 v138, v129
	v_add_u32_e32 v136, s88, v130
	v_ashrrev_i32_e32 v137, 31, v136
	v_lshl_add_u32 v134, v128, 3, s9
	v_lshlrev_b64 v[130:131], 11, v[136:137]
	v_ashrrev_i32_e32 v135, 31, v134
	v_lshl_add_u64 v[130:131], s[42:43], 0, v[130:131]
	v_lshl_add_u64 v[130:131], v[130:131], 0, v[134:135]
	global_load_dwordx2 v[178:179], v[130:131], off offset:1024
	global_load_dwordx2 v[180:181], v[130:131], off offset:1152
	v_lshl_add_u64 v[212:213], v[130:131], 0, s[46:47]
	global_load_dwordx2 v[182:183], v[212:213], off offset:1024
	global_load_dwordx2 v[184:185], v[212:213], off offset:1152
	v_lshl_add_u64 v[210:211], v[130:131], 0, s[48:49]
	global_load_dwordx2 v[186:187], v[210:211], off offset:1024
	global_load_dwordx2 v[188:189], v[210:211], off offset:1152
	v_lshl_add_u64 v[212:213], v[130:131], 0, s[14:15]
	global_load_dwordx2 v[190:191], v[212:213], off offset:1024
	global_load_dwordx2 v[192:193], v[212:213], off offset:1152
	v_lshl_add_u64 v[210:211], v[130:131], 0, s[50:51]
	global_load_dwordx2 v[194:195], v[210:211], off offset:1024
	global_load_dwordx2 v[196:197], v[210:211], off offset:1152
	v_lshl_add_u64 v[212:213], v[130:131], 0, s[54:55]
	global_load_dwordx2 v[198:199], v[212:213], off offset:1024
	global_load_dwordx2 v[200:201], v[212:213], off offset:1152
	v_lshl_add_u64 v[210:211], v[130:131], 0, s[56:57]
	global_load_dwordx2 v[202:203], v[210:211], off offset:1024
	global_load_dwordx2 v[204:205], v[210:211], off offset:1152
	v_lshl_add_u64 v[212:213], v[130:131], 0, s[58:59]
	global_load_dwordx2 v[206:207], v[212:213], off offset:1024
	global_load_dwordx2 v[208:209], v[212:213], off offset:1152
	s_and_b64 vcc, exec, s[44:45]
	s_cbranch_vccz .Lmy_ab_p3
	s_barrier
.Lmy_ab_p3:
	s_waitcnt vmcnt(14)
	v_mov_b64_e32 v[132:133], v[178:179]
	s_nop 0
	v_mov_b64_e32 v[130:131], v[180:181]
	v_lshlrev_b64 v[144:145], 10, v[136:137]
	v_mov_b32_e32 v139, v129
	v_mov_b32_e32 v140, v129
	v_mov_b32_e32 v141, v129
	v_add_u32_e32 v142, 16, v136
	v_ashrrev_i32_e32 v143, 31, v142
	v_lshl_add_u64 v[144:145], s[28:29], 0, v[144:145]
	v_lshlrev_b64 v[156:157], 11, v[142:143]
	v_lshl_add_u64 v[144:145], v[144:145], 0, v[134:135]
	s_and_b64 vcc, exec, s[2:3]
	s_mov_b64 s[2:3], -1
	v_cvt_f32_ubyte0_e32 v128, v132
	v_cvt_f32_ubyte1_e32 v137, v132
	v_cvt_f32_ubyte0_e32 v158, v133
	v_cvt_f32_ubyte1_e32 v159, v133
	v_cvt_f32_ubyte0_e32 v161, v130
	v_cvt_f32_ubyte1_e32 v162, v130
	v_cvt_f32_ubyte0_e32 v164, v131
	v_cvt_f32_ubyte1_e32 v165, v131
	v_max_f32_e32 v128, 0.5, v128
	v_max_f32_e32 v137, 0.5, v137
	v_max_f32_e32 v158, 0.5, v158
	v_max_f32_e32 v159, 0.5, v159
	v_max_f32_e32 v161, 0.5, v161
	v_max_f32_e32 v162, 0.5, v162
	v_max_f32_e32 v164, 0.5, v164
	v_max_f32_e32 v165, 0.5, v165
	v_mul_f32_e32 v128, 0x3a008081, v128
	v_mul_f32_e32 v137, 0x3a008081, v137
	v_mul_f32_e32 v158, 0x3a008081, v158
	v_mul_f32_e32 v159, 0x3a008081, v159
	v_mul_f32_e32 v161, 0x3a008081, v161
	v_mul_f32_e32 v162, 0x3a008081, v162
	v_mul_f32_e32 v164, 0x3a008081, v164
	v_mul_f32_e32 v165, 0x3a008081, v165
	v_mul_f32_e32 v112, v112, v128
	v_mul_f32_e32 v113, v113, v137
	v_mul_f32_e32 v116, v116, v158
	v_mul_f32_e32 v117, v117, v159
	v_cvt_f32_ubyte2_e32 v155, v132
	v_cvt_f32_ubyte3_e32 v132, v132
	v_cvt_f32_ubyte2_e32 v160, v133
	v_cvt_f32_ubyte3_e32 v133, v133
	v_mul_f32_e32 v120, v120, v161
	v_mul_f32_e32 v121, v121, v162
	v_mul_f32_e32 v124, v124, v164
	v_mul_f32_e32 v125, v125, v165
	v_cvt_pk_fp8_f32 v138, v112, v113
	v_cvt_pk_fp8_f32 v139, v116, v117
	v_cvt_f32_ubyte2_e32 v163, v130
	v_cvt_f32_ubyte3_e32 v130, v130
	v_cvt_f32_ubyte2_e32 v166, v131
	v_cvt_f32_ubyte3_e32 v131, v131
	v_max_f32_e32 v155, 0.5, v155
	v_max_f32_e32 v132, 0.5, v132
	v_max_f32_e32 v160, 0.5, v160
	v_max_f32_e32 v133, 0.5, v133
	v_cvt_pk_fp8_f32 v140, v120, v121
	v_cvt_pk_fp8_f32 v141, v124, v125
	v_max_f32_e32 v163, 0.5, v163
	v_max_f32_e32 v130, 0.5, v130
	v_max_f32_e32 v166, 0.5, v166
	v_max_f32_e32 v131, 0.5, v131
	v_mul_f32_e32 v155, 0x3a008081, v155
	v_mul_f32_e32 v132, 0x3a008081, v132
	v_mul_f32_e32 v160, 0x3a008081, v160
	v_mul_f32_e32 v133, 0x3a008081, v133
	v_mul_f32_e32 v163, 0x3a008081, v163
	v_mul_f32_e32 v130, 0x3a008081, v130
	v_mul_f32_e32 v166, 0x3a008081, v166
	v_mul_f32_e32 v131, 0x3a008081, v131
	v_mul_f32_e32 v114, v114, v155
	v_mul_f32_e32 v115, v115, v132
	v_mul_f32_e32 v118, v118, v160
	v_mul_f32_e32 v119, v119, v133
	v_mul_f32_e32 v122, v122, v163
	v_mul_f32_e32 v123, v123, v130
	v_mul_f32_e32 v126, v126, v166
	v_mul_f32_e32 v127, v127, v131
	v_cvt_pk_fp8_f32 v138, v114, v115 op_sel:[0,0,1]
	v_cvt_pk_fp8_f32 v139, v118, v119 op_sel:[0,0,1]
	v_cvt_pk_fp8_f32 v140, v122, v123 op_sel:[0,0,1]
	v_cvt_pk_fp8_f32 v141, v126, v127 op_sel:[0,0,1]
	v_lshl_add_u64 v[112:113], s[42:43], 0, v[156:157]
	global_store_dwordx2 v[144:145], v[138:139], off
	global_store_dwordx2 v[144:145], v[140:141], off offset:128
	v_lshl_add_u64 v[112:113], v[112:113], 0, v[134:135]
	s_waitcnt vmcnt(14)
; __device__ __forceinline__ unsigned pk4_fp8g(float a, float b, float c, float d) { int r = __builtin_amdgcn_cvt_pk_fp8_f32(a, b, 0, false); r = __builtin_amdgcn_cvt_pk_fp8_f32(c, d, r, true); return (unsigned)r; }
; #define G2B(bw, sh) (fmaxf((float)(((bw) >> (sh)) & 0xffu), 0.5f) * (1.f / 2040.f))
;     __device__ __forceinline__ void operator()(const f32x4 (&acc)[2][2][4][2], const Unit& u, int wr, int wc, int fr, int fq) const {
;     ...
;             for (int m = 0; m < 4; ++m) { const size_t r = (size_t)(row0 + ai * HALF + m * 16);
; #pragma unroll
;                 for (int bj = 0; bj < 2; ++bj) {
;                     const u32x2g b = *(const u32x2g*)(Gt + r * GC + DM + col0 + bj * HALF);
;                     f32x4 v0 = acc[ai][bj][m][0], v1 = acc[ai][bj][m][1];
;     ...
;                     v0[0] *= G2B(b.x, 0); v0[1] *= G2B(b.x, 8); v0[2] *= G2B(b.x, 16); v0[3] *= G2B(b.x, 24);
;                     v1[0] *= G2B(b.y, 0); v1[1] *= G2B(b.y, 8); v1[2] *= G2B(b.y, 16); v1[3] *= G2B(b.y, 24);
;     ...
;                     u32x2g w; w.x = pk4_fp8g(v0[0], v0[1], v0[2], v0[3]); w.y = pk4_fp8g(v1[0], v1[1], v1[2], v1[3]);
;                     *(u32x2g*)((unsigned char*)O + r * DM + col0 + bj * HALF) = w; }
	v_mov_b64_e32 v[114:115], v[182:183]
	s_nop 0
	v_mov_b64_e32 v[112:113], v[184:185]
	v_mov_b32_e32 v116, v129
	v_mov_b32_e32 v117, v129
	v_mov_b32_e32 v118, v129
	v_mov_b32_e32 v119, v129
	v_add_u32_e32 v120, 32, v136
	v_lshlrev_b64 v[122:123], 10, v[142:143]
	v_ashrrev_i32_e32 v121, 31, v120
	v_lshl_add_u64 v[122:123], s[28:29], 0, v[122:123]
	v_lshlrev_b64 v[124:125], 11, v[120:121]
	v_lshl_add_u64 v[124:125], s[42:43], 0, v[124:125]
	v_cvt_f32_ubyte0_e32 v126, v114
	v_cvt_f32_ubyte1_e32 v127, v114
	v_cvt_f32_ubyte0_e32 v130, v115
	v_cvt_f32_ubyte1_e32 v131, v115
	v_cvt_f32_ubyte0_e32 v133, v112
	v_cvt_f32_ubyte1_e32 v137, v112
	v_cvt_f32_ubyte0_e32 v139, v113
	v_cvt_f32_ubyte1_e32 v140, v113
	v_max_f32_e32 v126, 0.5, v126
	v_max_f32_e32 v127, 0.5, v127
	v_max_f32_e32 v130, 0.5, v130
	v_max_f32_e32 v131, 0.5, v131
	v_max_f32_e32 v133, 0.5, v133
	v_max_f32_e32 v137, 0.5, v137
	v_max_f32_e32 v139, 0.5, v139
	v_max_f32_e32 v140, 0.5, v140
	v_mul_f32_e32 v126, 0x3a008081, v126
	v_mul_f32_e32 v127, 0x3a008081, v127
	v_mul_f32_e32 v130, 0x3a008081, v130
	v_mul_f32_e32 v131, 0x3a008081, v131
	v_mul_f32_e32 v133, 0x3a008081, v133
	v_mul_f32_e32 v137, 0x3a008081, v137
	v_mul_f32_e32 v139, 0x3a008081, v139
	v_mul_f32_e32 v140, 0x3a008081, v140
	v_mul_f32_e32 v96, v96, v126
	v_mul_f32_e32 v97, v97, v127
	v_mul_f32_e32 v100, v100, v130
	v_mul_f32_e32 v101, v101, v131
	v_cvt_f32_ubyte2_e32 v128, v114
	v_cvt_f32_ubyte3_e32 v114, v114
	v_cvt_f32_ubyte2_e32 v132, v115
	v_cvt_f32_ubyte3_e32 v115, v115
	v_mul_f32_e32 v104, v104, v133
	v_mul_f32_e32 v105, v105, v137
	v_mul_f32_e32 v108, v108, v139
	v_mul_f32_e32 v109, v109, v140
	v_cvt_pk_fp8_f32 v116, v96, v97
	v_cvt_pk_fp8_f32 v117, v100, v101
	v_cvt_f32_ubyte2_e32 v138, v112
	v_cvt_f32_ubyte3_e32 v112, v112
	v_cvt_f32_ubyte2_e32 v141, v113
	v_cvt_f32_ubyte3_e32 v113, v113
	v_max_f32_e32 v128, 0.5, v128
	v_max_f32_e32 v114, 0.5, v114
	v_max_f32_e32 v132, 0.5, v132
	v_max_f32_e32 v115, 0.5, v115
	v_cvt_pk_fp8_f32 v118, v104, v105
	v_cvt_pk_fp8_f32 v119, v108, v109
	v_max_f32_e32 v138, 0.5, v138
	v_max_f32_e32 v112, 0.5, v112
	v_max_f32_e32 v141, 0.5, v141
	v_max_f32_e32 v113, 0.5, v113
	v_mul_f32_e32 v128, 0x3a008081, v128
	v_mul_f32_e32 v114, 0x3a008081, v114
	v_mul_f32_e32 v132, 0x3a008081, v132
	v_mul_f32_e32 v115, 0x3a008081, v115
	v_mul_f32_e32 v138, 0x3a008081, v138
	v_mul_f32_e32 v112, 0x3a008081, v112
	v_mul_f32_e32 v141, 0x3a008081, v141
	v_mul_f32_e32 v113, 0x3a008081, v113
	v_mul_f32_e32 v98, v98, v128
	v_mul_f32_e32 v99, v99, v114
	v_mul_f32_e32 v102, v102, v132
	v_mul_f32_e32 v103, v103, v115
	v_mul_f32_e32 v106, v106, v138
	v_mul_f32_e32 v107, v107, v112
	v_mul_f32_e32 v110, v110, v141
	v_mul_f32_e32 v111, v111, v113
	v_cvt_pk_fp8_f32 v116, v98, v99 op_sel:[0,0,1]
	v_cvt_pk_fp8_f32 v117, v102, v103 op_sel:[0,0,1]
	v_cvt_pk_fp8_f32 v118, v106, v107 op_sel:[0,0,1]
	v_cvt_pk_fp8_f32 v119, v110, v111 op_sel:[0,0,1]
	v_lshl_add_u64 v[96:97], v[122:123], 0, v[134:135]
	global_store_dwordx2 v[96:97], v[116:117], off
	global_store_dwordx2 v[96:97], v[118:119], off offset:128
	v_lshl_add_u64 v[98:99], v[124:125], 0, v[134:135]
	s_waitcnt vmcnt(14)
	v_mov_b64_e32 v[96:97], v[186:187]
	s_nop 0
	v_mov_b64_e32 v[98:99], v[188:189]
	v_lshlrev_b64 v[106:107], 10, v[120:121]
	v_mov_b32_e32 v100, v129
	v_mov_b32_e32 v101, v129
	v_mov_b32_e32 v102, v129
	v_mov_b32_e32 v103, v129
	v_add_u32_e32 v104, 48, v136
	v_ashrrev_i32_e32 v105, 31, v104
	v_lshl_add_u64 v[106:107], s[28:29], 0, v[106:107]
	v_lshlrev_b64 v[108:109], 11, v[104:105]
	v_lshl_add_u64 v[108:109], s[42:43], 0, v[108:109]
	v_cvt_f32_ubyte0_e32 v110, v96
	v_cvt_f32_ubyte1_e32 v111, v96
	v_cvt_f32_ubyte0_e32 v113, v97
	v_cvt_f32_ubyte1_e32 v114, v97
	v_cvt_f32_ubyte0_e32 v116, v98
	v_cvt_f32_ubyte1_e32 v117, v98
	v_cvt_f32_ubyte0_e32 v119, v99
	v_cvt_f32_ubyte1_e32 v120, v99
	v_max_f32_e32 v110, 0.5, v110
	v_max_f32_e32 v111, 0.5, v111
	v_max_f32_e32 v113, 0.5, v113
	v_max_f32_e32 v114, 0.5, v114
	v_max_f32_e32 v116, 0.5, v116
	v_max_f32_e32 v117, 0.5, v117
	v_max_f32_e32 v119, 0.5, v119
	v_max_f32_e32 v120, 0.5, v120
	v_mul_f32_e32 v110, 0x3a008081, v110
	v_mul_f32_e32 v111, 0x3a008081, v111
	v_mul_f32_e32 v113, 0x3a008081, v113
	v_mul_f32_e32 v114, 0x3a008081, v114
	v_mul_f32_e32 v116, 0x3a008081, v116
	v_mul_f32_e32 v117, 0x3a008081, v117
	v_mul_f32_e32 v119, 0x3a008081, v119
	v_mul_f32_e32 v120, 0x3a008081, v120
	v_mul_f32_e32 v80, v80, v110
	v_mul_f32_e32 v81, v81, v111
	v_mul_f32_e32 v84, v84, v113
	v_mul_f32_e32 v85, v85, v114
	v_cvt_f32_ubyte2_e32 v112, v96
	v_cvt_f32_ubyte3_e32 v96, v96
	v_cvt_f32_ubyte2_e32 v115, v97
	v_cvt_f32_ubyte3_e32 v97, v97
	v_mul_f32_e32 v88, v88, v116
	v_mul_f32_e32 v89, v89, v117
	v_mul_f32_e32 v92, v92, v119
	v_mul_f32_e32 v93, v93, v120
	v_cvt_pk_fp8_f32 v100, v80, v81
	v_cvt_pk_fp8_f32 v101, v84, v85
	v_cvt_f32_ubyte2_e32 v118, v98
	v_cvt_f32_ubyte3_e32 v98, v98
	v_cvt_f32_ubyte2_e32 v121, v99
	v_cvt_f32_ubyte3_e32 v99, v99
	v_max_f32_e32 v112, 0.5, v112
	v_max_f32_e32 v96, 0.5, v96
	v_max_f32_e32 v115, 0.5, v115
	v_max_f32_e32 v97, 0.5, v97
	v_cvt_pk_fp8_f32 v102, v88, v89
	v_cvt_pk_fp8_f32 v103, v92, v93
	v_max_f32_e32 v118, 0.5, v118
	v_max_f32_e32 v98, 0.5, v98
	v_max_f32_e32 v121, 0.5, v121
	v_max_f32_e32 v99, 0.5, v99
	v_mul_f32_e32 v112, 0x3a008081, v112
	v_mul_f32_e32 v96, 0x3a008081, v96
	v_mul_f32_e32 v115, 0x3a008081, v115
	v_mul_f32_e32 v97, 0x3a008081, v97
	v_mul_f32_e32 v118, 0x3a008081, v118
	v_mul_f32_e32 v98, 0x3a008081, v98
	v_mul_f32_e32 v121, 0x3a008081, v121
	v_mul_f32_e32 v99, 0x3a008081, v99
	v_mul_f32_e32 v82, v82, v112
	v_mul_f32_e32 v83, v83, v96
	v_mul_f32_e32 v86, v86, v115
	v_mul_f32_e32 v87, v87, v97
	v_mul_f32_e32 v90, v90, v118
	v_mul_f32_e32 v91, v91, v98
	v_mul_f32_e32 v94, v94, v121
	v_mul_f32_e32 v95, v95, v99
	v_cvt_pk_fp8_f32 v100, v82, v83 op_sel:[0,0,1]
	v_cvt_pk_fp8_f32 v101, v86, v87 op_sel:[0,0,1]
	v_cvt_pk_fp8_f32 v102, v90, v91 op_sel:[0,0,1]
	v_cvt_pk_fp8_f32 v103, v94, v95 op_sel:[0,0,1]
	v_lshl_add_u64 v[80:81], v[106:107], 0, v[134:135]
	global_store_dwordx2 v[80:81], v[100:101], off
	global_store_dwordx2 v[80:81], v[102:103], off offset:128
	v_lshl_add_u64 v[82:83], v[108:109], 0, v[134:135]
	s_waitcnt vmcnt(14)
; __device__ __forceinline__ unsigned pk4_fp8g(float a, float b, float c, float d) { int r = __builtin_amdgcn_cvt_pk_fp8_f32(a, b, 0, false); r = __builtin_amdgcn_cvt_pk_fp8_f32(c, d, r, true); return (unsigned)r; }
; #define G2B(bw, sh) (fmaxf((float)(((bw) >> (sh)) & 0xffu), 0.5f) * (1.f / 2040.f))
;     __device__ __forceinline__ void operator()(const f32x4 (&acc)[2][2][4][2], const Unit& u, int wr, int wc, int fr, int fq) const {
;     ...
;             for (int m = 0; m < 4; ++m) { const size_t r = (size_t)(row0 + ai * HALF + m * 16);
; #pragma unroll
;                 for (int bj = 0; bj < 2; ++bj) {
;                     const u32x2g b = *(const u32x2g*)(Gt + r * GC + DM + col0 + bj * HALF);
;                     f32x4 v0 = acc[ai][bj][m][0], v1 = acc[ai][bj][m][1];
;     ...
;                     v0[0] *= G2B(b.x, 0); v0[1] *= G2B(b.x, 8); v0[2] *= G2B(b.x, 16); v0[3] *= G2B(b.x, 24);
;                     v1[0] *= G2B(b.y, 0); v1[1] *= G2B(b.y, 8); v1[2] *= G2B(b.y, 16); v1[3] *= G2B(b.y, 24);
;     ...
;                     u32x2g w; w.x = pk4_fp8g(v0[0], v0[1], v0[2], v0[3]); w.y = pk4_fp8g(v1[0], v1[1], v1[2], v1[3]);
;                     *(u32x2g*)((unsigned char*)O + r * DM + col0 + bj * HALF) = w; }
	v_mov_b64_e32 v[80:81], v[190:191]
	s_nop 0
	v_mov_b64_e32 v[82:83], v[192:193]
	v_lshlrev_b64 v[90:91], 10, v[104:105]
	v_mov_b32_e32 v84, v129
	v_mov_b32_e32 v85, v129
	v_mov_b32_e32 v86, v129
	v_mov_b32_e32 v87, v129
	v_add_u32_e32 v88, 0x80, v136
	v_ashrrev_i32_e32 v89, 31, v88
	v_lshl_add_u64 v[90:91], s[28:29], 0, v[90:91]
	v_lshlrev_b64 v[92:93], 11, v[88:89]
	v_lshl_add_u64 v[92:93], s[42:43], 0, v[92:93]
	v_cvt_f32_ubyte0_e32 v94, v80
	v_cvt_f32_ubyte1_e32 v95, v80
	v_cvt_f32_ubyte0_e32 v97, v81
	v_cvt_f32_ubyte1_e32 v98, v81
	v_cvt_f32_ubyte0_e32 v100, v82
	v_cvt_f32_ubyte1_e32 v101, v82
	v_cvt_f32_ubyte0_e32 v103, v83
	v_cvt_f32_ubyte1_e32 v104, v83
	v_max_f32_e32 v94, 0.5, v94
	v_max_f32_e32 v95, 0.5, v95
	v_max_f32_e32 v97, 0.5, v97
	v_max_f32_e32 v98, 0.5, v98
	v_max_f32_e32 v100, 0.5, v100
	v_max_f32_e32 v101, 0.5, v101
	v_max_f32_e32 v103, 0.5, v103
	v_max_f32_e32 v104, 0.5, v104
	v_mul_f32_e32 v94, 0x3a008081, v94
	v_mul_f32_e32 v95, 0x3a008081, v95
	v_mul_f32_e32 v97, 0x3a008081, v97
	v_mul_f32_e32 v98, 0x3a008081, v98
	v_mul_f32_e32 v100, 0x3a008081, v100
	v_mul_f32_e32 v101, 0x3a008081, v101
	v_mul_f32_e32 v103, 0x3a008081, v103
	v_mul_f32_e32 v104, 0x3a008081, v104
	v_mul_f32_e32 v64, v64, v94
	v_mul_f32_e32 v65, v65, v95
	v_mul_f32_e32 v68, v68, v97
	v_mul_f32_e32 v69, v69, v98
	v_cvt_f32_ubyte2_e32 v96, v80
	v_cvt_f32_ubyte3_e32 v80, v80
	v_cvt_f32_ubyte2_e32 v99, v81
	v_cvt_f32_ubyte3_e32 v81, v81
	v_mul_f32_e32 v72, v72, v100
	v_mul_f32_e32 v73, v73, v101
	v_mul_f32_e32 v76, v76, v103
	v_mul_f32_e32 v77, v77, v104
	v_cvt_pk_fp8_f32 v84, v64, v65
	v_cvt_pk_fp8_f32 v85, v68, v69
	v_cvt_f32_ubyte2_e32 v102, v82
	v_cvt_f32_ubyte3_e32 v82, v82
	v_cvt_f32_ubyte2_e32 v105, v83
	v_cvt_f32_ubyte3_e32 v83, v83
	v_max_f32_e32 v96, 0.5, v96
	v_max_f32_e32 v80, 0.5, v80
	v_max_f32_e32 v99, 0.5, v99
	v_max_f32_e32 v81, 0.5, v81
	v_cvt_pk_fp8_f32 v86, v72, v73
	v_cvt_pk_fp8_f32 v87, v76, v77
	v_max_f32_e32 v102, 0.5, v102
	v_max_f32_e32 v82, 0.5, v82
	v_max_f32_e32 v105, 0.5, v105
	v_max_f32_e32 v83, 0.5, v83
	v_mul_f32_e32 v96, 0x3a008081, v96
	v_mul_f32_e32 v80, 0x3a008081, v80
	v_mul_f32_e32 v99, 0x3a008081, v99
	v_mul_f32_e32 v81, 0x3a008081, v81
	v_mul_f32_e32 v102, 0x3a008081, v102
	v_mul_f32_e32 v82, 0x3a008081, v82
	v_mul_f32_e32 v105, 0x3a008081, v105
	v_mul_f32_e32 v83, 0x3a008081, v83
	v_mul_f32_e32 v66, v66, v96
	v_mul_f32_e32 v67, v67, v80
	v_mul_f32_e32 v70, v70, v99
	v_mul_f32_e32 v71, v71, v81
	v_mul_f32_e32 v74, v74, v102
	v_mul_f32_e32 v75, v75, v82
	v_mul_f32_e32 v78, v78, v105
	v_mul_f32_e32 v79, v79, v83
	v_cvt_pk_fp8_f32 v84, v66, v67 op_sel:[0,0,1]
	v_cvt_pk_fp8_f32 v85, v70, v71 op_sel:[0,0,1]
	v_cvt_pk_fp8_f32 v86, v74, v75 op_sel:[0,0,1]
	v_cvt_pk_fp8_f32 v87, v78, v79 op_sel:[0,0,1]
	v_lshl_add_u64 v[64:65], v[90:91], 0, v[134:135]
	global_store_dwordx2 v[64:65], v[84:85], off
	global_store_dwordx2 v[64:65], v[86:87], off offset:128
	v_lshl_add_u64 v[66:67], v[92:93], 0, v[134:135]
	s_waitcnt vmcnt(14)
	v_mov_b64_e32 v[64:65], v[194:195]
	s_nop 0
	v_mov_b64_e32 v[66:67], v[196:197]
	v_lshlrev_b64 v[74:75], 10, v[88:89]
	v_mov_b32_e32 v68, v129
	v_mov_b32_e32 v69, v129
	v_mov_b32_e32 v70, v129
	v_mov_b32_e32 v71, v129
	v_add_u32_e32 v72, 0x90, v136
	v_ashrrev_i32_e32 v73, 31, v72
	v_lshl_add_u64 v[74:75], s[28:29], 0, v[74:75]
	v_lshlrev_b64 v[76:77], 11, v[72:73]
	v_lshl_add_u64 v[76:77], s[42:43], 0, v[76:77]
	v_cvt_f32_ubyte0_e32 v78, v64
	v_cvt_f32_ubyte1_e32 v79, v64
	v_cvt_f32_ubyte0_e32 v81, v65
	v_cvt_f32_ubyte1_e32 v82, v65
	v_cvt_f32_ubyte0_e32 v84, v66
	v_cvt_f32_ubyte1_e32 v85, v66
	v_cvt_f32_ubyte0_e32 v87, v67
	v_cvt_f32_ubyte1_e32 v88, v67
	v_max_f32_e32 v78, 0.5, v78
	v_max_f32_e32 v79, 0.5, v79
	v_max_f32_e32 v81, 0.5, v81
	v_max_f32_e32 v82, 0.5, v82
	v_max_f32_e32 v84, 0.5, v84
	v_max_f32_e32 v85, 0.5, v85
	v_max_f32_e32 v87, 0.5, v87
	v_max_f32_e32 v88, 0.5, v88
	v_mul_f32_e32 v78, 0x3a008081, v78
	v_mul_f32_e32 v79, 0x3a008081, v79
	v_mul_f32_e32 v81, 0x3a008081, v81
	v_mul_f32_e32 v82, 0x3a008081, v82
	v_mul_f32_e32 v84, 0x3a008081, v84
	v_mul_f32_e32 v85, 0x3a008081, v85
	v_mul_f32_e32 v87, 0x3a008081, v87
	v_mul_f32_e32 v88, 0x3a008081, v88
	v_mul_f32_e32 v48, v48, v78
	v_mul_f32_e32 v49, v49, v79
	v_mul_f32_e32 v52, v52, v81
	v_mul_f32_e32 v53, v53, v82
	v_cvt_f32_ubyte2_e32 v80, v64
	v_cvt_f32_ubyte3_e32 v64, v64
	v_cvt_f32_ubyte2_e32 v83, v65
	v_cvt_f32_ubyte3_e32 v65, v65
	v_mul_f32_e32 v56, v56, v84
	v_mul_f32_e32 v57, v57, v85
	v_mul_f32_e32 v60, v60, v87
	v_mul_f32_e32 v61, v61, v88
	v_cvt_pk_fp8_f32 v68, v48, v49
	v_cvt_pk_fp8_f32 v69, v52, v53
	v_cvt_f32_ubyte2_e32 v86, v66
	v_cvt_f32_ubyte3_e32 v66, v66
	v_cvt_f32_ubyte2_e32 v89, v67
	v_cvt_f32_ubyte3_e32 v67, v67
	v_max_f32_e32 v80, 0.5, v80
	v_max_f32_e32 v64, 0.5, v64
	v_max_f32_e32 v83, 0.5, v83
	v_max_f32_e32 v65, 0.5, v65
	v_cvt_pk_fp8_f32 v70, v56, v57
	v_cvt_pk_fp8_f32 v71, v60, v61
	v_max_f32_e32 v86, 0.5, v86
	v_max_f32_e32 v66, 0.5, v66
	v_max_f32_e32 v89, 0.5, v89
	v_max_f32_e32 v67, 0.5, v67
	v_mul_f32_e32 v80, 0x3a008081, v80
	v_mul_f32_e32 v64, 0x3a008081, v64
	v_mul_f32_e32 v83, 0x3a008081, v83
	v_mul_f32_e32 v65, 0x3a008081, v65
	v_mul_f32_e32 v86, 0x3a008081, v86
	v_mul_f32_e32 v66, 0x3a008081, v66
	v_mul_f32_e32 v89, 0x3a008081, v89
	v_mul_f32_e32 v67, 0x3a008081, v67
	v_mul_f32_e32 v50, v50, v80
	v_mul_f32_e32 v51, v51, v64
	v_mul_f32_e32 v54, v54, v83
	v_mul_f32_e32 v55, v55, v65
	v_mul_f32_e32 v58, v58, v86
	v_mul_f32_e32 v59, v59, v66
	v_mul_f32_e32 v62, v62, v89
	v_mul_f32_e32 v63, v63, v67
	v_cvt_pk_fp8_f32 v68, v50, v51 op_sel:[0,0,1]
	v_cvt_pk_fp8_f32 v69, v54, v55 op_sel:[0,0,1]
	v_cvt_pk_fp8_f32 v70, v58, v59 op_sel:[0,0,1]
	v_cvt_pk_fp8_f32 v71, v62, v63 op_sel:[0,0,1]
	v_lshl_add_u64 v[48:49], v[74:75], 0, v[134:135]
	global_store_dwordx2 v[48:49], v[68:69], off
	global_store_dwordx2 v[48:49], v[70:71], off offset:128
	v_lshl_add_u64 v[50:51], v[76:77], 0, v[134:135]
	s_waitcnt vmcnt(14)
; __device__ __forceinline__ unsigned pk4_fp8g(float a, float b, float c, float d) { int r = __builtin_amdgcn_cvt_pk_fp8_f32(a, b, 0, false); r = __builtin_amdgcn_cvt_pk_fp8_f32(c, d, r, true); return (unsigned)r; }
; #define G2B(bw, sh) (fmaxf((float)(((bw) >> (sh)) & 0xffu), 0.5f) * (1.f / 2040.f))
;     __device__ __forceinline__ void operator()(const f32x4 (&acc)[2][2][4][2], const Unit& u, int wr, int wc, int fr, int fq) const {
;     ...
;             for (int m = 0; m < 4; ++m) { const size_t r = (size_t)(row0 + ai * HALF + m * 16);
; #pragma unroll
;                 for (int bj = 0; bj < 2; ++bj) {
;                     const u32x2g b = *(const u32x2g*)(Gt + r * GC + DM + col0 + bj * HALF);
;                     f32x4 v0 = acc[ai][bj][m][0], v1 = acc[ai][bj][m][1];
;     ...
;                     v0[0] *= G2B(b.x, 0); v0[1] *= G2B(b.x, 8); v0[2] *= G2B(b.x, 16); v0[3] *= G2B(b.x, 24);
;                     v1[0] *= G2B(b.y, 0); v1[1] *= G2B(b.y, 8); v1[2] *= G2B(b.y, 16); v1[3] *= G2B(b.y, 24);
;     ...
;                     u32x2g w; w.x = pk4_fp8g(v0[0], v0[1], v0[2], v0[3]); w.y = pk4_fp8g(v1[0], v1[1], v1[2], v1[3]);
;                     *(u32x2g*)((unsigned char*)O + r * DM + col0 + bj * HALF) = w; }
	v_mov_b64_e32 v[48:49], v[198:199]
	s_nop 0
	v_mov_b64_e32 v[50:51], v[200:201]
	v_lshlrev_b64 v[58:59], 10, v[72:73]
	v_mov_b32_e32 v52, v129
	v_mov_b32_e32 v53, v129
	v_mov_b32_e32 v54, v129
	v_mov_b32_e32 v55, v129
	v_add_u32_e32 v56, 0xa0, v136
	v_ashrrev_i32_e32 v57, 31, v56
	v_lshl_add_u64 v[58:59], s[28:29], 0, v[58:59]
	v_lshlrev_b64 v[60:61], 11, v[56:57]
	v_lshl_add_u64 v[60:61], s[42:43], 0, v[60:61]
	v_cvt_f32_ubyte0_e32 v62, v48
	v_cvt_f32_ubyte1_e32 v63, v48
	v_cvt_f32_ubyte0_e32 v65, v49
	v_cvt_f32_ubyte1_e32 v66, v49
	v_cvt_f32_ubyte0_e32 v68, v50
	v_cvt_f32_ubyte1_e32 v69, v50
	v_cvt_f32_ubyte0_e32 v71, v51
	v_cvt_f32_ubyte1_e32 v72, v51
	v_max_f32_e32 v62, 0.5, v62
	v_max_f32_e32 v63, 0.5, v63
	v_max_f32_e32 v65, 0.5, v65
	v_max_f32_e32 v66, 0.5, v66
	v_max_f32_e32 v68, 0.5, v68
	v_max_f32_e32 v69, 0.5, v69
	v_max_f32_e32 v71, 0.5, v71
	v_max_f32_e32 v72, 0.5, v72
	v_mul_f32_e32 v62, 0x3a008081, v62
	v_mul_f32_e32 v63, 0x3a008081, v63
	v_mul_f32_e32 v65, 0x3a008081, v65
	v_mul_f32_e32 v66, 0x3a008081, v66
	v_mul_f32_e32 v68, 0x3a008081, v68
	v_mul_f32_e32 v69, 0x3a008081, v69
	v_mul_f32_e32 v71, 0x3a008081, v71
	v_mul_f32_e32 v72, 0x3a008081, v72
	v_mul_f32_e32 v32, v32, v62
	v_mul_f32_e32 v33, v33, v63
	v_mul_f32_e32 v36, v36, v65
	v_mul_f32_e32 v37, v37, v66
	v_cvt_f32_ubyte2_e32 v64, v48
	v_cvt_f32_ubyte3_e32 v48, v48
	v_cvt_f32_ubyte2_e32 v67, v49
	v_cvt_f32_ubyte3_e32 v49, v49
	v_mul_f32_e32 v40, v40, v68
	v_mul_f32_e32 v41, v41, v69
	v_mul_f32_e32 v44, v44, v71
	v_mul_f32_e32 v45, v45, v72
	v_cvt_pk_fp8_f32 v52, v32, v33
	v_cvt_pk_fp8_f32 v53, v36, v37
	v_cvt_f32_ubyte2_e32 v70, v50
	v_cvt_f32_ubyte3_e32 v50, v50
	v_cvt_f32_ubyte2_e32 v73, v51
	v_cvt_f32_ubyte3_e32 v51, v51
	v_max_f32_e32 v64, 0.5, v64
	v_max_f32_e32 v48, 0.5, v48
	v_max_f32_e32 v67, 0.5, v67
	v_max_f32_e32 v49, 0.5, v49
	v_cvt_pk_fp8_f32 v54, v40, v41
	v_cvt_pk_fp8_f32 v55, v44, v45
	v_max_f32_e32 v70, 0.5, v70
	v_max_f32_e32 v50, 0.5, v50
	v_max_f32_e32 v73, 0.5, v73
	v_max_f32_e32 v51, 0.5, v51
	v_mul_f32_e32 v64, 0x3a008081, v64
	v_mul_f32_e32 v48, 0x3a008081, v48
	v_mul_f32_e32 v67, 0x3a008081, v67
	v_mul_f32_e32 v49, 0x3a008081, v49
	v_mul_f32_e32 v70, 0x3a008081, v70
	v_mul_f32_e32 v50, 0x3a008081, v50
	v_mul_f32_e32 v73, 0x3a008081, v73
	v_mul_f32_e32 v51, 0x3a008081, v51
	v_mul_f32_e32 v34, v34, v64
	v_mul_f32_e32 v35, v35, v48
	v_mul_f32_e32 v38, v38, v67
	v_mul_f32_e32 v39, v39, v49
	v_mul_f32_e32 v42, v42, v70
	v_mul_f32_e32 v43, v43, v50
	v_mul_f32_e32 v46, v46, v73
	v_mul_f32_e32 v47, v47, v51
	v_cvt_pk_fp8_f32 v52, v34, v35 op_sel:[0,0,1]
	v_cvt_pk_fp8_f32 v53, v38, v39 op_sel:[0,0,1]
	v_cvt_pk_fp8_f32 v54, v42, v43 op_sel:[0,0,1]
	v_cvt_pk_fp8_f32 v55, v46, v47 op_sel:[0,0,1]
	v_lshl_add_u64 v[32:33], v[58:59], 0, v[134:135]
	global_store_dwordx2 v[32:33], v[52:53], off
	global_store_dwordx2 v[32:33], v[54:55], off offset:128
	v_lshl_add_u64 v[34:35], v[60:61], 0, v[134:135]
	s_waitcnt vmcnt(14)
	v_mov_b64_e32 v[32:33], v[202:203]
	s_nop 0
	v_mov_b64_e32 v[34:35], v[204:205]
	v_lshlrev_b64 v[42:43], 10, v[56:57]
	v_mov_b32_e32 v36, v129
	v_mov_b32_e32 v37, v129
	v_mov_b32_e32 v38, v129
	v_mov_b32_e32 v39, v129
	v_add_u32_e32 v40, 0xb0, v136
	v_ashrrev_i32_e32 v41, 31, v40
	v_lshl_add_u64 v[42:43], s[28:29], 0, v[42:43]
	v_lshlrev_b64 v[44:45], 11, v[40:41]
	v_lshl_add_u64 v[44:45], s[42:43], 0, v[44:45]
	v_cvt_f32_ubyte0_e32 v46, v32
	v_cvt_f32_ubyte1_e32 v47, v32
	v_cvt_f32_ubyte0_e32 v49, v33
	v_cvt_f32_ubyte1_e32 v50, v33
	v_cvt_f32_ubyte0_e32 v52, v34
	v_cvt_f32_ubyte1_e32 v53, v34
	v_cvt_f32_ubyte0_e32 v55, v35
	v_cvt_f32_ubyte1_e32 v56, v35
	v_max_f32_e32 v46, 0.5, v46
	v_max_f32_e32 v47, 0.5, v47
	v_max_f32_e32 v49, 0.5, v49
	v_max_f32_e32 v50, 0.5, v50
	v_max_f32_e32 v52, 0.5, v52
	v_max_f32_e32 v53, 0.5, v53
	v_max_f32_e32 v55, 0.5, v55
	v_max_f32_e32 v56, 0.5, v56
	v_mul_f32_e32 v46, 0x3a008081, v46
	v_mul_f32_e32 v47, 0x3a008081, v47
	v_mul_f32_e32 v49, 0x3a008081, v49
	v_mul_f32_e32 v50, 0x3a008081, v50
	v_mul_f32_e32 v52, 0x3a008081, v52
	v_mul_f32_e32 v53, 0x3a008081, v53
	v_mul_f32_e32 v55, 0x3a008081, v55
	v_mul_f32_e32 v56, 0x3a008081, v56
	v_mul_f32_e32 v16, v16, v46
	v_mul_f32_e32 v17, v17, v47
	v_mul_f32_e32 v20, v20, v49
	v_mul_f32_e32 v21, v21, v50
	v_cvt_f32_ubyte2_e32 v48, v32
	v_cvt_f32_ubyte3_e32 v32, v32
	v_cvt_f32_ubyte2_e32 v51, v33
	v_cvt_f32_ubyte3_e32 v33, v33
	v_mul_f32_e32 v24, v24, v52
	v_mul_f32_e32 v25, v25, v53
	v_mul_f32_e32 v28, v28, v55
	v_mul_f32_e32 v29, v29, v56
	v_cvt_pk_fp8_f32 v36, v16, v17
	v_cvt_pk_fp8_f32 v37, v20, v21
	v_cvt_f32_ubyte2_e32 v54, v34
	v_cvt_f32_ubyte3_e32 v34, v34
	v_cvt_f32_ubyte2_e32 v57, v35
	v_cvt_f32_ubyte3_e32 v35, v35
	v_max_f32_e32 v48, 0.5, v48
	v_max_f32_e32 v32, 0.5, v32
	v_max_f32_e32 v51, 0.5, v51
	v_max_f32_e32 v33, 0.5, v33
	v_cvt_pk_fp8_f32 v38, v24, v25
	v_cvt_pk_fp8_f32 v39, v28, v29
	v_max_f32_e32 v54, 0.5, v54
	v_max_f32_e32 v34, 0.5, v34
	v_max_f32_e32 v57, 0.5, v57
	v_max_f32_e32 v35, 0.5, v35
	v_mul_f32_e32 v48, 0x3a008081, v48
	v_mul_f32_e32 v32, 0x3a008081, v32
	v_mul_f32_e32 v51, 0x3a008081, v51
	v_mul_f32_e32 v33, 0x3a008081, v33
	v_mul_f32_e32 v54, 0x3a008081, v54
	v_mul_f32_e32 v34, 0x3a008081, v34
	v_mul_f32_e32 v57, 0x3a008081, v57
	v_mul_f32_e32 v35, 0x3a008081, v35
	v_mul_f32_e32 v18, v18, v48
	v_mul_f32_e32 v19, v19, v32
	v_mul_f32_e32 v22, v22, v51
	v_mul_f32_e32 v23, v23, v33
	v_mul_f32_e32 v26, v26, v54
	v_mul_f32_e32 v27, v27, v34
	v_mul_f32_e32 v30, v30, v57
	v_mul_f32_e32 v31, v31, v35
	v_cvt_pk_fp8_f32 v36, v18, v19 op_sel:[0,0,1]
	v_cvt_pk_fp8_f32 v37, v22, v23 op_sel:[0,0,1]
	v_cvt_pk_fp8_f32 v38, v26, v27 op_sel:[0,0,1]
	v_cvt_pk_fp8_f32 v39, v30, v31 op_sel:[0,0,1]
	v_lshl_add_u64 v[16:17], v[42:43], 0, v[134:135]
	global_store_dwordx2 v[16:17], v[36:37], off
	global_store_dwordx2 v[16:17], v[38:39], off offset:128
	v_lshl_add_u64 v[18:19], v[44:45], 0, v[134:135]
	s_waitcnt vmcnt(14)
; __device__ __forceinline__ unsigned pk4_fp8g(float a, float b, float c, float d) { int r = __builtin_amdgcn_cvt_pk_fp8_f32(a, b, 0, false); r = __builtin_amdgcn_cvt_pk_fp8_f32(c, d, r, true); return (unsigned)r; }
; #define G2B(bw, sh) (fmaxf((float)(((bw) >> (sh)) & 0xffu), 0.5f) * (1.f / 2040.f))
; template <class Epi, class Sched, bool ALIGN_EPI = false, bool SP2 = false, bool FP8 = false>
; __device__ __forceinline__ void gemm_phase(PG8_LAS unsigned char* lds, const Gemm g, const Sched& S, const Epi& E) {
;     ...
; #pragma unroll
;         for (int a = 0; a < 2; ++a)
; #pragma unroll
;             for (int b = 0; b < 2; ++b)
; #pragma unroll
;                 for (int m = 0; m < 4; ++m)
; #pragma unroll
;                     for (int n = 0; n < 2; ++n) { acc[a][b][m][n] = (f32x4){0.f, 0.f, 0.f, 0.f}; if constexpr (FP8) asm volatile("" : "+v"(acc[a][b][m][n])); }
;         cur = nxt; cA = nA; cB = nB; ++ui;
;     __device__ __forceinline__ void operator()(const f32x4 (&acc)[2][2][4][2], const Unit& u, int wr, int wc, int fr, int fq) const {
;     ...
;             for (int m = 0; m < 4; ++m) { const size_t r = (size_t)(row0 + ai * HALF + m * 16);
; #pragma unroll
;                 for (int bj = 0; bj < 2; ++bj) {
;                     const u32x2g b = *(const u32x2g*)(Gt + r * GC + DM + col0 + bj * HALF);
;                     f32x4 v0 = acc[ai][bj][m][0], v1 = acc[ai][bj][m][1];
;     ...
;                     v0[0] *= G2B(b.x, 0); v0[1] *= G2B(b.x, 8); v0[2] *= G2B(b.x, 16); v0[3] *= G2B(b.x, 24);
;                     v1[0] *= G2B(b.y, 0); v1[1] *= G2B(b.y, 8); v1[2] *= G2B(b.y, 16); v1[3] *= G2B(b.y, 24);
;     ...
;                     u32x2g w; w.x = pk4_fp8g(v0[0], v0[1], v0[2], v0[3]); w.y = pk4_fp8g(v1[0], v1[1], v1[2], v1[3]);
;                     *(u32x2g*)((unsigned char*)O + r * DM + col0 + bj * HALF) = w; }
;                 asm volatile("" ::: "memory"); }
	v_mov_b64_e32 v[16:17], v[206:207]
	s_nop 0
	v_mov_b64_e32 v[18:19], v[208:209]
	v_mov_b32_e32 v20, v129
	v_mov_b32_e32 v21, v129
	v_mov_b32_e32 v22, v129
	v_mov_b32_e32 v23, v129
	v_lshlrev_b64 v[24:25], 10, v[40:41]
	v_cvt_f32_ubyte0_e32 v26, v16
	v_cvt_f32_ubyte1_e32 v27, v16
	v_cvt_f32_ubyte0_e32 v29, v17
	v_cvt_f32_ubyte1_e32 v30, v17
	v_cvt_f32_ubyte0_e32 v32, v18
	v_cvt_f32_ubyte1_e32 v33, v18
	v_cvt_f32_ubyte0_e32 v35, v19
	v_cvt_f32_ubyte1_e32 v36, v19
	v_max_f32_e32 v26, 0.5, v26
	v_max_f32_e32 v27, 0.5, v27
	v_max_f32_e32 v29, 0.5, v29
	v_max_f32_e32 v30, 0.5, v30
	v_max_f32_e32 v32, 0.5, v32
	v_max_f32_e32 v33, 0.5, v33
	v_max_f32_e32 v35, 0.5, v35
	v_max_f32_e32 v36, 0.5, v36
	v_mul_f32_e32 v26, 0x3a008081, v26
	v_mul_f32_e32 v27, 0x3a008081, v27
	v_mul_f32_e32 v29, 0x3a008081, v29
	v_mul_f32_e32 v30, 0x3a008081, v30
	v_mul_f32_e32 v32, 0x3a008081, v32
	v_mul_f32_e32 v33, 0x3a008081, v33
	v_mul_f32_e32 v35, 0x3a008081, v35
	v_mul_f32_e32 v36, 0x3a008081, v36
	v_mul_f32_e32 v4, v4, v26
	v_mul_f32_e32 v5, v5, v27
	v_mul_f32_e32 v8, v8, v29
	v_mul_f32_e32 v9, v9, v30
	v_cvt_f32_ubyte2_e32 v28, v16
	v_cvt_f32_ubyte3_e32 v16, v16
	v_cvt_f32_ubyte2_e32 v31, v17
	v_cvt_f32_ubyte3_e32 v17, v17
	v_mul_f32_e32 v12, v12, v32
	v_mul_f32_e32 v13, v13, v33
	v_mul_f32_e32 v0, v0, v35
	v_mul_f32_e32 v1, v1, v36
	v_cvt_pk_fp8_f32 v20, v4, v5
	v_cvt_pk_fp8_f32 v21, v8, v9
	v_cvt_f32_ubyte2_e32 v34, v18
	v_cvt_f32_ubyte3_e32 v18, v18
	v_cvt_f32_ubyte2_e32 v37, v19
	v_cvt_f32_ubyte3_e32 v19, v19
	v_max_f32_e32 v28, 0.5, v28
	v_max_f32_e32 v16, 0.5, v16
	v_max_f32_e32 v31, 0.5, v31
	v_max_f32_e32 v17, 0.5, v17
	v_cvt_pk_fp8_f32 v22, v12, v13
	v_cvt_pk_fp8_f32 v23, v0, v1
	v_max_f32_e32 v34, 0.5, v34
	v_max_f32_e32 v18, 0.5, v18
	v_max_f32_e32 v37, 0.5, v37
	v_max_f32_e32 v19, 0.5, v19
	v_mul_f32_e32 v28, 0x3a008081, v28
	v_mul_f32_e32 v16, 0x3a008081, v16
	v_mul_f32_e32 v31, 0x3a008081, v31
	v_mul_f32_e32 v17, 0x3a008081, v17
	v_mul_f32_e32 v34, 0x3a008081, v34
	v_mul_f32_e32 v18, 0x3a008081, v18
	v_mul_f32_e32 v37, 0x3a008081, v37
	v_mul_f32_e32 v19, 0x3a008081, v19
	v_mul_f32_e32 v6, v6, v28
	v_mul_f32_e32 v7, v7, v16
	v_mul_f32_e32 v10, v10, v31
	v_mul_f32_e32 v11, v11, v17
	v_mul_f32_e32 v14, v14, v34
	v_mul_f32_e32 v15, v15, v18
	v_mul_f32_e32 v2, v2, v37
	v_mul_f32_e32 v3, v3, v19
	v_cvt_pk_fp8_f32 v20, v6, v7 op_sel:[0,0,1]
	v_cvt_pk_fp8_f32 v21, v10, v11 op_sel:[0,0,1]
	v_cvt_pk_fp8_f32 v22, v14, v15 op_sel:[0,0,1]
	v_cvt_pk_fp8_f32 v23, v2, v3 op_sel:[0,0,1]
	v_lshl_add_u64 v[0:1], s[28:29], 0, v[24:25]
	v_lshl_add_u64 v[0:1], v[0:1], 0, v[134:135]
	global_store_dwordx2 v[0:1], v[20:21], off
	global_store_dwordx2 v[0:1], v[22:23], off offset:128
	s_cbranch_vccnz .LBB0_297
	s_mov_b32 s9, s8
	s_mov_b32 s10, s8
	s_mov_b32 s11, s8
	v_mov_b64_e32 v[0:1], s[8:9]
	v_mov_b64_e32 v[114:115], s[10:11]
	v_mov_b64_e32 v[118:119], s[10:11]
	v_mov_b64_e32 v[98:99], s[10:11]
	v_mov_b64_e32 v[102:103], s[10:11]
	v_mov_b64_e32 v[82:83], s[10:11]
	v_mov_b64_e32 v[86:87], s[10:11]
	v_mov_b64_e32 v[66:67], s[10:11]
	v_mov_b64_e32 v[70:71], s[10:11]
	v_mov_b64_e32 v[122:123], s[10:11]
	v_mov_b64_e32 v[126:127], s[10:11]
	v_mov_b64_e32 v[106:107], s[10:11]
	v_mov_b64_e32 v[110:111], s[10:11]
	v_mov_b64_e32 v[90:91], s[10:11]
	v_mov_b64_e32 v[94:95], s[10:11]
	v_mov_b64_e32 v[74:75], s[10:11]
	v_mov_b64_e32 v[78:79], s[10:11]
	v_mov_b64_e32 v[50:51], s[10:11]
	v_mov_b64_e32 v[54:55], s[10:11]
	v_mov_b64_e32 v[34:35], s[10:11]
	v_mov_b64_e32 v[38:39], s[10:11]
	v_mov_b64_e32 v[18:19], s[10:11]
	v_mov_b64_e32 v[22:23], s[10:11]
	v_mov_b64_e32 v[4:5], s[8:9]
	v_mov_b64_e32 v[8:9], s[8:9]
	v_mov_b64_e32 v[58:59], s[10:11]
	v_mov_b64_e32 v[62:63], s[10:11]
	v_mov_b64_e32 v[42:43], s[10:11]
	v_mov_b64_e32 v[46:47], s[10:11]
	v_mov_b64_e32 v[26:27], s[10:11]
	v_mov_b64_e32 v[30:31], s[10:11]
	v_mov_b64_e32 v[14:15], s[10:11]
	v_mov_b64_e32 v[2:3], s[10:11]
	v_mov_b64_e32 v[112:113], s[8:9]
	v_mov_b64_e32 v[116:117], s[8:9]
	v_mov_b64_e32 v[96:97], s[8:9]
	v_mov_b64_e32 v[100:101], s[8:9]
	v_mov_b64_e32 v[80:81], s[8:9]
	v_mov_b64_e32 v[84:85], s[8:9]
	v_mov_b64_e32 v[64:65], s[8:9]
	v_mov_b64_e32 v[68:69], s[8:9]
	v_mov_b64_e32 v[120:121], s[8:9]
	v_mov_b64_e32 v[124:125], s[8:9]
	v_mov_b64_e32 v[104:105], s[8:9]
	v_mov_b64_e32 v[108:109], s[8:9]
	v_mov_b64_e32 v[88:89], s[8:9]
	v_mov_b64_e32 v[92:93], s[8:9]
	v_mov_b64_e32 v[72:73], s[8:9]
	v_mov_b64_e32 v[76:77], s[8:9]
	v_mov_b64_e32 v[48:49], s[8:9]
	v_mov_b64_e32 v[52:53], s[8:9]
	v_mov_b64_e32 v[32:33], s[8:9]
	v_mov_b64_e32 v[36:37], s[8:9]
	v_mov_b64_e32 v[16:17], s[8:9]
	v_mov_b64_e32 v[20:21], s[8:9]
	v_mov_b64_e32 v[6:7], s[10:11]
	v_mov_b64_e32 v[10:11], s[10:11]
	v_mov_b64_e32 v[56:57], s[8:9]
	v_mov_b64_e32 v[60:61], s[8:9]
	v_mov_b64_e32 v[40:41], s[8:9]
	v_mov_b64_e32 v[44:45], s[8:9]
	v_mov_b64_e32 v[24:25], s[8:9]
	v_mov_b64_e32 v[28:29], s[8:9]
	v_mov_b64_e32 v[12:13], s[8:9]
	s_andn2_b64 vcc, exec, s[12:13]
	s_cbranch_vccnz .LBB0_296
	s_mov_b32 s100, 1
	s_branch .LBB0_296

; __device__ __forceinline__ unsigned cvt_pk_bf16(float lo, float hi) { const f32x2c_t v = {lo, hi}; const bf16x2c_t b = __builtin_convertvector(v, bf16x2c_t); return __builtin_bit_cast(unsigned, b); }
; #define PG8_BAR __builtin_amdgcn_s_barrier()
; template <class Epi, class Sched, bool ALIGN_EPI = false, bool SP2 = false, bool FP8 = false>
; __device__ __forceinline__ void gemm_phase(PG8_LAS unsigned char* lds, const Gemm g, const Sched& S, const Epi& E) {
;     ...
;         if constexpr (ALIGN_EPI) { if (wr == 0) PG8_BAR; }
;     __device__ __forceinline__ void operator()(const f32x4 (&acc)[2][2][4][2], const Unit& u, int wr, int wc, int fr, int fq) const {
;         { int l_ = (int)(threadIdx.x & 63u); asm volatile("" : "+v"(l_)); fr = l_ & 15; fq = l_ >> 4; }
;         const int row0 = u.pm * BM + wr * 64 + fr, col0 = u.pn * BM + wc * 32 + 8 * fq;
;         const float* xbase = (u.pm * BM < TP) ? xp : (xs - (size_t)TP * DM);
; #pragma unroll
;         for (int ai = 0; ai < 2; ++ai) {
;             f32x4 xv[4][2][2];
; #pragma unroll
;             for (int m = 0; m < 4; ++m)
; #pragma unroll
;                 for (int bj = 0; bj < 2; ++bj) { const size_t off = (size_t)(row0 + ai * HALF + m * 16) * DM + col0 + bj * HALF; xv[m][bj][0] = *(const f32x4*)(xbase + off); xv[m][bj][1] = *(const f32x4*)(xbase + off + 4); }
; #pragma unroll
;             for (int m = 0; m < 4; ++m) { const size_t r = (size_t)(row0 + ai * HALF + m * 16); float ss = 0.f;
; #pragma unroll
;                 for (int bj = 0; bj < 2; ++bj) { const size_t off = r * DM + col0 + bj * HALF;
;                     const f32x4 v0 = acc[ai][bj][m][0] * ascale + xv[m][bj][0], v1 = acc[ai][bj][m][1] * ascale + xv[m][bj][1];
;                     if (!WB) { *(f32x4*)(out + off) = v0; *(f32x4*)(out + off + 4) = v1; }
;                     if (WB) { u32x4 w; w.x = cvt_pk_bf16(v0[0], v0[1]); w.y = cvt_pk_bf16(v0[2], v0[3]); w.z = cvt_pk_bf16(v1[0], v1[1]); w.w = cvt_pk_bf16(v1[2], v1[3]); *(u32x4*)(xb + off) = w; }
;                     ss += (v0[0] * v0[0] + v0[1] * v0[1]) + (v0[2] * v0[2] + v0[3] * v0[3]) + (v1[0] * v1[0] + v1[1] * v1[1]) + (v1[2] * v1[2] + v1[3] * v1[3]); }
;                 ss += __shfl_xor(ss, 16); ss += __shfl_xor(ss, 32);
;                 if (fq == 0) ssq[r * 16 + u.pn * 4 + wc] = ss; }
.LBB0_345:
	s_lshl_b32 s0, s52, 8
	v_and_b32_e32 v178, 63, v254
	s_add_i32 s0, s0, s64
	v_and_or_b32 v196, v178, 15, s0
	s_lshl_b32 s0, s50, 8
	s_or_b32 s0, s0, s65
	v_ashrrev_i32_e32 v207, 1, v178
	v_and_b32_e32 v207, -8, v207
	v_add_u32_e32 v207, s0, v207
	s_cmp_lt_i32 s52, 64
	s_cselect_b32 s0, s37, s62
	s_cselect_b32 s1, s36, s61
	v_mov_b32_e32 v252, s1
	v_mov_b32_e32 v253, s0
	v_mov_b32_e32 v224, v196
	v_ashrrev_i32_e32 v225, 31, v196
	v_mov_b32_e32 v226, v207
	v_ashrrev_i32_e32 v227, 31, v207
	v_lshl_add_u64 v[252:253], v[226:227], 2, v[252:253]
	v_lshlrev_b64 v[250:251], 12, v[224:225]
	v_lshl_add_u64 v[252:253], v[252:253], 0, v[250:251]
	s_lshl_b32 s0, s50, 4
	s_lshl_b32 s1, s63, 2
	s_add_u32 s0, s0, s1
	s_mov_b32 s1, 0
	v_lshlrev_b64 v[248:249], 6, v[224:225]
	v_lshl_add_u64 v[248:249], s[12:13], 0, v[248:249]
	v_lshl_add_u64 v[248:249], v[248:249], 0, s[0:1]
	v_lshlrev_b64 v[250:251], 11, v[224:225]
	v_lshl_add_u64 v[250:251], s[16:17], 0, v[250:251]
	v_lshl_add_u64 v[224:225], v[226:227], 1, v[250:251]
	v_mov_b64_e32 v[226:227], v[248:249]
	s_mov_b64 s[78:79], 0x10000
	s_mov_b64 s[80:81], 0x50000
	s_mov_b64 s[82:83], 0x8000
	s_mov_b64 s[84:85], 0x28000
	s_mov_b64 s[86:87], 0x400
	s_mov_b64 s[88:89], 0x1400
	global_load_dwordx4 v[128:131], v[252:253], off
	global_load_dwordx4 v[132:135], v[252:253], off offset:16
	global_load_dwordx4 v[136:139], v[252:253], off offset:512
	global_load_dwordx4 v[140:143], v[252:253], off offset:528
	v_lshl_add_u64 v[252:253], v[252:253], 0, s[78:79]
	global_load_dwordx4 v[144:147], v[252:253], off
	global_load_dwordx4 v[148:151], v[252:253], off offset:16
	global_load_dwordx4 v[152:155], v[252:253], off offset:512
	global_load_dwordx4 v[156:159], v[252:253], off offset:528
	v_lshl_add_u64 v[252:253], v[252:253], 0, s[78:79]
	global_load_dwordx4 v[160:163], v[252:253], off
	global_load_dwordx4 v[164:167], v[252:253], off offset:16
	global_load_dwordx4 v[168:171], v[252:253], off offset:512
	global_load_dwordx4 v[172:175], v[252:253], off offset:528
	v_lshl_add_u64 v[252:253], v[252:253], 0, s[78:79]
	global_load_dwordx4 v[180:183], v[252:253], off
	global_load_dwordx4 v[184:187], v[252:253], off offset:16
	global_load_dwordx4 v[188:191], v[252:253], off offset:512
	global_load_dwordx4 v[192:195], v[252:253], off offset:528
	v_lshl_add_u64 v[252:253], v[252:253], 0, s[80:81]
	global_load_dwordx4 v[208:211], v[252:253], off
	global_load_dwordx4 v[212:215], v[252:253], off offset:16
	global_load_dwordx4 v[216:219], v[252:253], off offset:512
	global_load_dwordx4 v[220:223], v[252:253], off offset:528
	v_lshl_add_u64 v[252:253], v[252:253], 0, s[78:79]
	global_load_dwordx4 v[236:239], v[252:253], off
	global_load_dwordx4 v[240:243], v[252:253], off offset:16
	global_load_dwordx4 v[244:247], v[252:253], off offset:512
	global_load_dwordx4 v[248:251], v[252:253], off offset:528
	v_lshl_add_u64 v[252:253], v[252:253], 0, s[78:79]
	s_and_b64 vcc, exec, s[38:39]
	s_cbranch_vccz .Lmy_ab_p4
	s_barrier
.Lmy_ab_p4:
	v_and_b32_e32 v196, 64, v204
	v_add_u32_e32 v196, 64, v196
	v_xor_b32_e32 v205, 16, v204
	v_cmp_lt_i32_e32 vcc, v205, v196
	s_nop 1
	v_cndmask_b32_e32 v205, v204, v205, vcc
	v_lshlrev_b32_e32 v205, 2, v205
	v_xor_b32_e32 v206, 32, v204
	v_cmp_lt_i32_e32 vcc, v206, v196
	s_nop 1
	v_cndmask_b32_e32 v206, v204, v206, vcc
	v_lshlrev_b32_e32 v206, 2, v206
	v_cmp_gt_u32_e32 vcc, 16, v178
	s_waitcnt vmcnt(20)
	v_pk_fma_f32 v[116:117], v[116:117], s[40:41], v[128:129] op_sel_hi:[1,0,1]
	v_pk_fma_f32 v[118:119], v[118:119], s[40:41], v[130:131] op_sel_hi:[1,0,1]
	v_pk_fma_f32 v[112:113], v[112:113], s[40:41], v[132:133] op_sel_hi:[1,0,1]
	v_pk_fma_f32 v[114:115], v[114:115], s[40:41], v[134:135] op_sel_hi:[1,0,1]
	v_pk_fma_f32 v[124:125], v[124:125], s[40:41], v[136:137] op_sel_hi:[1,0,1]
	v_pk_fma_f32 v[126:127], v[126:127], s[40:41], v[138:139] op_sel_hi:[1,0,1]
	v_pk_fma_f32 v[120:121], v[120:121], s[40:41], v[140:141] op_sel_hi:[1,0,1]
	v_pk_fma_f32 v[122:123], v[122:123], s[40:41], v[142:143] op_sel_hi:[1,0,1]
	v_mul_f32_e32 v128, v117, v117
	v_mul_f32_e32 v129, v119, v119
	v_mul_f32_e32 v130, v113, v113
	v_mul_f32_e32 v131, v115, v115
	v_mul_f32_e32 v132, v125, v125
	v_mul_f32_e32 v133, v127, v127
	v_mul_f32_e32 v134, v121, v121
	v_mul_f32_e32 v135, v123, v123
	v_fmac_f32_e32 v128, v116, v116
	v_fmac_f32_e32 v129, v118, v118
	v_fmac_f32_e32 v130, v112, v112
	v_fmac_f32_e32 v131, v114, v114
	v_fmac_f32_e32 v132, v124, v124
	v_fmac_f32_e32 v133, v126, v126
	v_fmac_f32_e32 v134, v120, v120
	v_fmac_f32_e32 v135, v122, v122
	v_cvt_pk_bf16_f32 v136, v116, v117
	v_cvt_pk_bf16_f32 v137, v118, v119
	v_cvt_pk_bf16_f32 v138, v112, v113
	v_cvt_pk_bf16_f32 v139, v114, v115
	v_cvt_pk_bf16_f32 v140, v124, v125
	v_cvt_pk_bf16_f32 v141, v126, v127
	v_cvt_pk_bf16_f32 v142, v120, v121
	v_cvt_pk_bf16_f32 v143, v122, v123
	global_store_dwordx4 v[224:225], v[136:139], off
	global_store_dwordx4 v[224:225], v[140:143], off offset:256
	v_add_f32_e32 v128, v128, v129
	v_add_f32_e32 v130, v130, v131
	v_add_f32_e32 v132, v132, v133
	v_add_f32_e32 v134, v134, v135
	v_add_f32_e32 v128, v128, v130
	v_add_f32_e32 v132, v132, v134
	v_add_f32_e32 v128, v128, v132
	ds_bpermute_b32 v129, v205, v128
	s_waitcnt lgkmcnt(0)
	v_add_f32_e32 v128, v128, v129
	ds_bpermute_b32 v129, v206, v128
	s_waitcnt lgkmcnt(0)
	v_add_f32_e32 v128, v128, v129
	s_and_saveexec_b64 s[50:51], vcc
	global_store_dword v[226:227], v128, off
	s_or_b64 exec, exec, s[50:51]
	v_lshl_add_u64 v[224:225], v[224:225], 0, s[82:83]
	v_lshl_add_u64 v[226:227], v[226:227], 0, s[86:87]
	global_load_dwordx4 v[128:131], v[252:253], off
	global_load_dwordx4 v[132:135], v[252:253], off offset:16
	global_load_dwordx4 v[136:139], v[252:253], off offset:512
	global_load_dwordx4 v[140:143], v[252:253], off offset:528
	v_lshl_add_u64 v[252:253], v[252:253], 0, s[78:79]
	s_waitcnt vmcnt(23)
; __device__ __forceinline__ unsigned cvt_pk_bf16(float lo, float hi) { const f32x2c_t v = {lo, hi}; const bf16x2c_t b = __builtin_convertvector(v, bf16x2c_t); return __builtin_bit_cast(unsigned, b); }
;     __device__ __forceinline__ void operator()(const f32x4 (&acc)[2][2][4][2], const Unit& u, int wr, int wc, int fr, int fq) const {
;     ...
;                 for (int bj = 0; bj < 2; ++bj) { const size_t off = (size_t)(row0 + ai * HALF + m * 16) * DM + col0 + bj * HALF; xv[m][bj][0] = *(const f32x4*)(xbase + off); xv[m][bj][1] = *(const f32x4*)(xbase + off + 4); }
; #pragma unroll
;             for (int m = 0; m < 4; ++m) { const size_t r = (size_t)(row0 + ai * HALF + m * 16); float ss = 0.f;
; #pragma unroll
;                 for (int bj = 0; bj < 2; ++bj) { const size_t off = r * DM + col0 + bj * HALF;
;                     const f32x4 v0 = acc[ai][bj][m][0] * ascale + xv[m][bj][0], v1 = acc[ai][bj][m][1] * ascale + xv[m][bj][1];
;                     if (!WB) { *(f32x4*)(out + off) = v0; *(f32x4*)(out + off + 4) = v1; }
;                     if (WB) { u32x4 w; w.x = cvt_pk_bf16(v0[0], v0[1]); w.y = cvt_pk_bf16(v0[2], v0[3]); w.z = cvt_pk_bf16(v1[0], v1[1]); w.w = cvt_pk_bf16(v1[2], v1[3]); *(u32x4*)(xb + off) = w; }
;                     ss += (v0[0] * v0[0] + v0[1] * v0[1]) + (v0[2] * v0[2] + v0[3] * v0[3]) + (v1[0] * v1[0] + v1[1] * v1[1]) + (v1[2] * v1[2] + v1[3] * v1[3]); }
;                 ss += __shfl_xor(ss, 16); ss += __shfl_xor(ss, 32);
;                 if (fq == 0) ssq[r * 16 + u.pn * 4 + wc] = ss; }
	v_pk_fma_f32 v[108:109], v[108:109], s[40:41], v[144:145] op_sel_hi:[1,0,1]
	v_pk_fma_f32 v[110:111], v[110:111], s[40:41], v[146:147] op_sel_hi:[1,0,1]
	v_pk_fma_f32 v[100:101], v[100:101], s[40:41], v[148:149] op_sel_hi:[1,0,1]
	v_pk_fma_f32 v[102:103], v[102:103], s[40:41], v[150:151] op_sel_hi:[1,0,1]
	v_pk_fma_f32 v[104:105], v[104:105], s[40:41], v[152:153] op_sel_hi:[1,0,1]
	v_pk_fma_f32 v[106:107], v[106:107], s[40:41], v[154:155] op_sel_hi:[1,0,1]
	v_pk_fma_f32 v[96:97], v[96:97], s[40:41], v[156:157] op_sel_hi:[1,0,1]
	v_pk_fma_f32 v[98:99], v[98:99], s[40:41], v[158:159] op_sel_hi:[1,0,1]
	v_mul_f32_e32 v144, v109, v109
	v_mul_f32_e32 v145, v111, v111
	v_mul_f32_e32 v146, v101, v101
	v_mul_f32_e32 v147, v103, v103
	v_mul_f32_e32 v148, v105, v105
	v_mul_f32_e32 v149, v107, v107
	v_mul_f32_e32 v150, v97, v97
	v_mul_f32_e32 v151, v99, v99
	v_fmac_f32_e32 v144, v108, v108
	v_fmac_f32_e32 v145, v110, v110
	v_fmac_f32_e32 v146, v100, v100
	v_fmac_f32_e32 v147, v102, v102
	v_fmac_f32_e32 v148, v104, v104
	v_fmac_f32_e32 v149, v106, v106
	v_fmac_f32_e32 v150, v96, v96
	v_fmac_f32_e32 v151, v98, v98
	v_cvt_pk_bf16_f32 v152, v108, v109
	v_cvt_pk_bf16_f32 v153, v110, v111
	v_cvt_pk_bf16_f32 v154, v100, v101
	v_cvt_pk_bf16_f32 v155, v102, v103
	v_cvt_pk_bf16_f32 v156, v104, v105
	v_cvt_pk_bf16_f32 v157, v106, v107
	v_cvt_pk_bf16_f32 v158, v96, v97
	v_cvt_pk_bf16_f32 v159, v98, v99
	global_store_dwordx4 v[224:225], v[152:155], off
	global_store_dwordx4 v[224:225], v[156:159], off offset:256
	v_add_f32_e32 v144, v144, v145
	v_add_f32_e32 v146, v146, v147
	v_add_f32_e32 v148, v148, v149
	v_add_f32_e32 v150, v150, v151
	v_add_f32_e32 v144, v144, v146
	v_add_f32_e32 v148, v148, v150
	v_add_f32_e32 v144, v144, v148
	ds_bpermute_b32 v145, v205, v144
	s_waitcnt lgkmcnt(0)
	v_add_f32_e32 v144, v144, v145
	ds_bpermute_b32 v145, v206, v144
	s_waitcnt lgkmcnt(0)
	v_add_f32_e32 v144, v144, v145
	s_and_saveexec_b64 s[50:51], vcc
	global_store_dword v[226:227], v144, off
	s_or_b64 exec, exec, s[50:51]
	v_lshl_add_u64 v[224:225], v[224:225], 0, s[82:83]
	v_lshl_add_u64 v[226:227], v[226:227], 0, s[86:87]
	global_load_dwordx4 v[144:147], v[252:253], off
	global_load_dwordx4 v[148:151], v[252:253], off offset:16
	global_load_dwordx4 v[152:155], v[252:253], off offset:512
	global_load_dwordx4 v[156:159], v[252:253], off offset:528
	s_waitcnt vmcnt(26)
	v_pk_fma_f32 v[92:93], v[92:93], s[40:41], v[160:161] op_sel_hi:[1,0,1]
	v_pk_fma_f32 v[94:95], v[94:95], s[40:41], v[162:163] op_sel_hi:[1,0,1]
	v_pk_fma_f32 v[84:85], v[84:85], s[40:41], v[164:165] op_sel_hi:[1,0,1]
	v_pk_fma_f32 v[86:87], v[86:87], s[40:41], v[166:167] op_sel_hi:[1,0,1]
	v_pk_fma_f32 v[88:89], v[88:89], s[40:41], v[168:169] op_sel_hi:[1,0,1]
	v_pk_fma_f32 v[90:91], v[90:91], s[40:41], v[170:171] op_sel_hi:[1,0,1]
	v_pk_fma_f32 v[80:81], v[80:81], s[40:41], v[172:173] op_sel_hi:[1,0,1]
	v_pk_fma_f32 v[82:83], v[82:83], s[40:41], v[174:175] op_sel_hi:[1,0,1]
	v_mul_f32_e32 v160, v93, v93
	v_mul_f32_e32 v161, v95, v95
	v_mul_f32_e32 v162, v85, v85
	v_mul_f32_e32 v163, v87, v87
	v_mul_f32_e32 v164, v89, v89
	v_mul_f32_e32 v165, v91, v91
	v_mul_f32_e32 v166, v81, v81
	v_mul_f32_e32 v167, v83, v83
	v_fmac_f32_e32 v160, v92, v92
	v_fmac_f32_e32 v161, v94, v94
	v_fmac_f32_e32 v162, v84, v84
	v_fmac_f32_e32 v163, v86, v86
	v_fmac_f32_e32 v164, v88, v88
	v_fmac_f32_e32 v165, v90, v90
	v_fmac_f32_e32 v166, v80, v80
	v_fmac_f32_e32 v167, v82, v82
	v_cvt_pk_bf16_f32 v168, v92, v93
	v_cvt_pk_bf16_f32 v169, v94, v95
	v_cvt_pk_bf16_f32 v170, v84, v85
	v_cvt_pk_bf16_f32 v171, v86, v87
	v_cvt_pk_bf16_f32 v172, v88, v89
	v_cvt_pk_bf16_f32 v173, v90, v91
	v_cvt_pk_bf16_f32 v174, v80, v81
	v_cvt_pk_bf16_f32 v175, v82, v83
	global_store_dwordx4 v[224:225], v[168:171], off
	global_store_dwordx4 v[224:225], v[172:175], off offset:256
	v_add_f32_e32 v160, v160, v161
	v_add_f32_e32 v162, v162, v163
	v_add_f32_e32 v164, v164, v165
	v_add_f32_e32 v166, v166, v167
	v_add_f32_e32 v160, v160, v162
	v_add_f32_e32 v164, v164, v166
	v_add_f32_e32 v160, v160, v164
	ds_bpermute_b32 v161, v205, v160
	s_waitcnt lgkmcnt(0)
	v_add_f32_e32 v160, v160, v161
	ds_bpermute_b32 v161, v206, v160
	s_waitcnt lgkmcnt(0)
	v_add_f32_e32 v160, v160, v161
	s_and_saveexec_b64 s[50:51], vcc
	global_store_dword v[226:227], v160, off
	s_or_b64 exec, exec, s[50:51]
	v_lshl_add_u64 v[224:225], v[224:225], 0, s[82:83]
	v_lshl_add_u64 v[226:227], v[226:227], 0, s[86:87]
	s_waitcnt vmcnt(25)
	v_pk_fma_f32 v[76:77], v[76:77], s[40:41], v[180:181] op_sel_hi:[1,0,1]
	v_pk_fma_f32 v[78:79], v[78:79], s[40:41], v[182:183] op_sel_hi:[1,0,1]
	v_pk_fma_f32 v[68:69], v[68:69], s[40:41], v[184:185] op_sel_hi:[1,0,1]
	v_pk_fma_f32 v[70:71], v[70:71], s[40:41], v[186:187] op_sel_hi:[1,0,1]
	v_pk_fma_f32 v[72:73], v[72:73], s[40:41], v[188:189] op_sel_hi:[1,0,1]
	v_pk_fma_f32 v[74:75], v[74:75], s[40:41], v[190:191] op_sel_hi:[1,0,1]
	v_pk_fma_f32 v[64:65], v[64:65], s[40:41], v[192:193] op_sel_hi:[1,0,1]
	v_pk_fma_f32 v[66:67], v[66:67], s[40:41], v[194:195] op_sel_hi:[1,0,1]
	v_mul_f32_e32 v180, v77, v77
	v_mul_f32_e32 v181, v79, v79
	v_mul_f32_e32 v182, v69, v69
	v_mul_f32_e32 v183, v71, v71
	v_mul_f32_e32 v184, v73, v73
	v_mul_f32_e32 v185, v75, v75
	v_mul_f32_e32 v186, v65, v65
	v_mul_f32_e32 v187, v67, v67
	v_fmac_f32_e32 v180, v76, v76
	v_fmac_f32_e32 v181, v78, v78
	v_fmac_f32_e32 v182, v68, v68
	v_fmac_f32_e32 v183, v70, v70
	v_fmac_f32_e32 v184, v72, v72
	v_fmac_f32_e32 v185, v74, v74
	v_fmac_f32_e32 v186, v64, v64
	v_fmac_f32_e32 v187, v66, v66
	v_cvt_pk_bf16_f32 v188, v76, v77
	v_cvt_pk_bf16_f32 v189, v78, v79
	v_cvt_pk_bf16_f32 v190, v68, v69
	v_cvt_pk_bf16_f32 v191, v70, v71
	v_cvt_pk_bf16_f32 v192, v72, v73
	v_cvt_pk_bf16_f32 v193, v74, v75
	v_cvt_pk_bf16_f32 v194, v64, v65
	v_cvt_pk_bf16_f32 v195, v66, v67
	global_store_dwordx4 v[224:225], v[188:191], off
	global_store_dwordx4 v[224:225], v[192:195], off offset:256
	v_add_f32_e32 v180, v180, v181
	v_add_f32_e32 v182, v182, v183
	v_add_f32_e32 v184, v184, v185
	v_add_f32_e32 v186, v186, v187
	v_add_f32_e32 v180, v180, v182
	v_add_f32_e32 v184, v184, v186
	v_add_f32_e32 v180, v180, v184
	ds_bpermute_b32 v181, v205, v180
	s_waitcnt lgkmcnt(0)
; __device__ __forceinline__ unsigned cvt_pk_bf16(float lo, float hi) { const f32x2c_t v = {lo, hi}; const bf16x2c_t b = __builtin_convertvector(v, bf16x2c_t); return __builtin_bit_cast(unsigned, b); }
;     __device__ __forceinline__ void operator()(const f32x4 (&acc)[2][2][4][2], const Unit& u, int wr, int wc, int fr, int fq) const {
;     ...
;                 for (int bj = 0; bj < 2; ++bj) { const size_t off = (size_t)(row0 + ai * HALF + m * 16) * DM + col0 + bj * HALF; xv[m][bj][0] = *(const f32x4*)(xbase + off); xv[m][bj][1] = *(const f32x4*)(xbase + off + 4); }
; #pragma unroll
;             for (int m = 0; m < 4; ++m) { const size_t r = (size_t)(row0 + ai * HALF + m * 16); float ss = 0.f;
; #pragma unroll
;                 for (int bj = 0; bj < 2; ++bj) { const size_t off = r * DM + col0 + bj * HALF;
;                     const f32x4 v0 = acc[ai][bj][m][0] * ascale + xv[m][bj][0], v1 = acc[ai][bj][m][1] * ascale + xv[m][bj][1];
;                     if (!WB) { *(f32x4*)(out + off) = v0; *(f32x4*)(out + off + 4) = v1; }
;                     if (WB) { u32x4 w; w.x = cvt_pk_bf16(v0[0], v0[1]); w.y = cvt_pk_bf16(v0[2], v0[3]); w.z = cvt_pk_bf16(v1[0], v1[1]); w.w = cvt_pk_bf16(v1[2], v1[3]); *(u32x4*)(xb + off) = w; }
;                     ss += (v0[0] * v0[0] + v0[1] * v0[1]) + (v0[2] * v0[2] + v0[3] * v0[3]) + (v1[0] * v1[0] + v1[1] * v1[1]) + (v1[2] * v1[2] + v1[3] * v1[3]); }
;                 ss += __shfl_xor(ss, 16); ss += __shfl_xor(ss, 32);
;                 if (fq == 0) ssq[r * 16 + u.pn * 4 + wc] = ss; }
	v_add_f32_e32 v180, v180, v181
	ds_bpermute_b32 v181, v206, v180
	s_waitcnt lgkmcnt(0)
	v_add_f32_e32 v180, v180, v181
	s_and_saveexec_b64 s[50:51], vcc
	global_store_dword v[226:227], v180, off
	s_or_b64 exec, exec, s[50:51]
	v_lshl_add_u64 v[224:225], v[224:225], 0, s[84:85]
	v_lshl_add_u64 v[226:227], v[226:227], 0, s[88:89]
	s_waitcnt vmcnt(24)
	v_pk_fma_f32 v[52:53], v[52:53], s[40:41], v[208:209] op_sel_hi:[1,0,1]
	v_pk_fma_f32 v[54:55], v[54:55], s[40:41], v[210:211] op_sel_hi:[1,0,1]
	v_pk_fma_f32 v[48:49], v[48:49], s[40:41], v[212:213] op_sel_hi:[1,0,1]
	v_pk_fma_f32 v[50:51], v[50:51], s[40:41], v[214:215] op_sel_hi:[1,0,1]
	v_pk_fma_f32 v[60:61], v[60:61], s[40:41], v[216:217] op_sel_hi:[1,0,1]
	v_pk_fma_f32 v[62:63], v[62:63], s[40:41], v[218:219] op_sel_hi:[1,0,1]
	v_pk_fma_f32 v[56:57], v[56:57], s[40:41], v[220:221] op_sel_hi:[1,0,1]
	v_pk_fma_f32 v[58:59], v[58:59], s[40:41], v[222:223] op_sel_hi:[1,0,1]
	v_mul_f32_e32 v208, v53, v53
	v_mul_f32_e32 v209, v55, v55
	v_mul_f32_e32 v210, v49, v49
	v_mul_f32_e32 v211, v51, v51
	v_mul_f32_e32 v212, v61, v61
	v_mul_f32_e32 v213, v63, v63
	v_mul_f32_e32 v214, v57, v57
	v_mul_f32_e32 v215, v59, v59
	v_fmac_f32_e32 v208, v52, v52
	v_fmac_f32_e32 v209, v54, v54
	v_fmac_f32_e32 v210, v48, v48
	v_fmac_f32_e32 v211, v50, v50
	v_fmac_f32_e32 v212, v60, v60
	v_fmac_f32_e32 v213, v62, v62
	v_fmac_f32_e32 v214, v56, v56
	v_fmac_f32_e32 v215, v58, v58
	v_cvt_pk_bf16_f32 v216, v52, v53
	v_cvt_pk_bf16_f32 v217, v54, v55
	v_cvt_pk_bf16_f32 v218, v48, v49
	v_cvt_pk_bf16_f32 v219, v50, v51
	v_cvt_pk_bf16_f32 v220, v60, v61
	v_cvt_pk_bf16_f32 v221, v62, v63
	v_cvt_pk_bf16_f32 v222, v56, v57
	v_cvt_pk_bf16_f32 v223, v58, v59
	global_store_dwordx4 v[224:225], v[216:219], off
	global_store_dwordx4 v[224:225], v[220:223], off offset:256
	v_add_f32_e32 v208, v208, v209
	v_add_f32_e32 v210, v210, v211
	v_add_f32_e32 v212, v212, v213
	v_add_f32_e32 v214, v214, v215
	v_add_f32_e32 v208, v208, v210
	v_add_f32_e32 v212, v212, v214
	v_add_f32_e32 v208, v208, v212
	ds_bpermute_b32 v209, v205, v208
	s_waitcnt lgkmcnt(0)
	v_add_f32_e32 v208, v208, v209
	ds_bpermute_b32 v209, v206, v208
	s_waitcnt lgkmcnt(0)
	v_add_f32_e32 v208, v208, v209
	s_and_saveexec_b64 s[50:51], vcc
	global_store_dword v[226:227], v208, off
	s_or_b64 exec, exec, s[50:51]
	v_lshl_add_u64 v[224:225], v[224:225], 0, s[82:83]
	v_lshl_add_u64 v[226:227], v[226:227], 0, s[86:87]
	s_waitcnt vmcnt(23)
	v_pk_fma_f32 v[44:45], v[44:45], s[40:41], v[236:237] op_sel_hi:[1,0,1]
	v_pk_fma_f32 v[46:47], v[46:47], s[40:41], v[238:239] op_sel_hi:[1,0,1]
	v_pk_fma_f32 v[36:37], v[36:37], s[40:41], v[240:241] op_sel_hi:[1,0,1]
	v_pk_fma_f32 v[38:39], v[38:39], s[40:41], v[242:243] op_sel_hi:[1,0,1]
	v_pk_fma_f32 v[40:41], v[40:41], s[40:41], v[244:245] op_sel_hi:[1,0,1]
	v_pk_fma_f32 v[42:43], v[42:43], s[40:41], v[246:247] op_sel_hi:[1,0,1]
	v_pk_fma_f32 v[32:33], v[32:33], s[40:41], v[248:249] op_sel_hi:[1,0,1]
	v_pk_fma_f32 v[34:35], v[34:35], s[40:41], v[250:251] op_sel_hi:[1,0,1]
	v_mul_f32_e32 v236, v45, v45
	v_mul_f32_e32 v237, v47, v47
	v_mul_f32_e32 v238, v37, v37
	v_mul_f32_e32 v239, v39, v39
	v_mul_f32_e32 v240, v41, v41
	v_mul_f32_e32 v241, v43, v43
	v_mul_f32_e32 v242, v33, v33
	v_mul_f32_e32 v243, v35, v35
	v_fmac_f32_e32 v236, v44, v44
	v_fmac_f32_e32 v237, v46, v46
	v_fmac_f32_e32 v238, v36, v36
	v_fmac_f32_e32 v239, v38, v38
	v_fmac_f32_e32 v240, v40, v40
	v_fmac_f32_e32 v241, v42, v42
	v_fmac_f32_e32 v242, v32, v32
	v_fmac_f32_e32 v243, v34, v34
	v_cvt_pk_bf16_f32 v244, v44, v45
	v_cvt_pk_bf16_f32 v245, v46, v47
	v_cvt_pk_bf16_f32 v246, v36, v37
	v_cvt_pk_bf16_f32 v247, v38, v39
	v_cvt_pk_bf16_f32 v248, v40, v41
	v_cvt_pk_bf16_f32 v249, v42, v43
	v_cvt_pk_bf16_f32 v250, v32, v33
	v_cvt_pk_bf16_f32 v251, v34, v35
	global_store_dwordx4 v[224:225], v[244:247], off
	global_store_dwordx4 v[224:225], v[248:251], off offset:256
	v_add_f32_e32 v236, v236, v237
	v_add_f32_e32 v238, v238, v239
	v_add_f32_e32 v240, v240, v241
	v_add_f32_e32 v242, v242, v243
	v_add_f32_e32 v236, v236, v238
	v_add_f32_e32 v240, v240, v242
	v_add_f32_e32 v236, v236, v240
	ds_bpermute_b32 v237, v205, v236
	s_waitcnt lgkmcnt(0)
	v_add_f32_e32 v236, v236, v237
	ds_bpermute_b32 v237, v206, v236
	s_waitcnt lgkmcnt(0)
	v_add_f32_e32 v236, v236, v237
	s_and_saveexec_b64 s[50:51], vcc
	global_store_dword v[226:227], v236, off
	s_or_b64 exec, exec, s[50:51]
	v_lshl_add_u64 v[224:225], v[224:225], 0, s[82:83]
	v_lshl_add_u64 v[226:227], v[226:227], 0, s[86:87]
	s_waitcnt vmcnt(19)
	v_pk_fma_f32 v[28:29], v[28:29], s[40:41], v[128:129] op_sel_hi:[1,0,1]
	v_pk_fma_f32 v[30:31], v[30:31], s[40:41], v[130:131] op_sel_hi:[1,0,1]
	v_pk_fma_f32 v[20:21], v[20:21], s[40:41], v[132:133] op_sel_hi:[1,0,1]
	v_pk_fma_f32 v[22:23], v[22:23], s[40:41], v[134:135] op_sel_hi:[1,0,1]
	v_pk_fma_f32 v[24:25], v[24:25], s[40:41], v[136:137] op_sel_hi:[1,0,1]
	v_pk_fma_f32 v[26:27], v[26:27], s[40:41], v[138:139] op_sel_hi:[1,0,1]
	v_pk_fma_f32 v[16:17], v[16:17], s[40:41], v[140:141] op_sel_hi:[1,0,1]
	v_pk_fma_f32 v[18:19], v[18:19], s[40:41], v[142:143] op_sel_hi:[1,0,1]
	v_mul_f32_e32 v128, v29, v29
	v_mul_f32_e32 v129, v31, v31
	v_mul_f32_e32 v130, v21, v21
	v_mul_f32_e32 v131, v23, v23
	v_mul_f32_e32 v132, v25, v25
	v_mul_f32_e32 v133, v27, v27
	v_mul_f32_e32 v134, v17, v17
	v_mul_f32_e32 v135, v19, v19
	v_fmac_f32_e32 v128, v28, v28
	v_fmac_f32_e32 v129, v30, v30
	v_fmac_f32_e32 v130, v20, v20
	v_fmac_f32_e32 v131, v22, v22
	v_fmac_f32_e32 v132, v24, v24
	v_fmac_f32_e32 v133, v26, v26
	v_fmac_f32_e32 v134, v16, v16
	v_fmac_f32_e32 v135, v18, v18
	v_cvt_pk_bf16_f32 v136, v28, v29
	v_cvt_pk_bf16_f32 v137, v30, v31
	v_cvt_pk_bf16_f32 v138, v20, v21
	v_cvt_pk_bf16_f32 v139, v22, v23
	v_cvt_pk_bf16_f32 v140, v24, v25
	v_cvt_pk_bf16_f32 v141, v26, v27
	v_cvt_pk_bf16_f32 v142, v16, v17
	v_cvt_pk_bf16_f32 v143, v18, v19
	global_store_dwordx4 v[224:225], v[136:139], off
	global_store_dwordx4 v[224:225], v[140:143], off offset:256
	v_add_f32_e32 v128, v128, v129
	v_add_f32_e32 v130, v130, v131
	v_add_f32_e32 v132, v132, v133
	v_add_f32_e32 v134, v134, v135
	v_add_f32_e32 v128, v128, v130
	v_add_f32_e32 v132, v132, v134
	v_add_f32_e32 v128, v128, v132
	ds_bpermute_b32 v129, v205, v128
	s_waitcnt lgkmcnt(0)
; __device__ __forceinline__ unsigned cvt_pk_bf16(float lo, float hi) { const f32x2c_t v = {lo, hi}; const bf16x2c_t b = __builtin_convertvector(v, bf16x2c_t); return __builtin_bit_cast(unsigned, b); }
; template <class Epi, class Sched, bool ALIGN_EPI = false, bool SP2 = false, bool FP8 = false>
; __device__ __forceinline__ void gemm_phase(PG8_LAS unsigned char* lds, const Gemm g, const Sched& S, const Epi& E) {
;     ...
; #pragma unroll
;         for (int a = 0; a < 2; ++a)
; #pragma unroll
;             for (int b = 0; b < 2; ++b)
; #pragma unroll
;                 for (int m = 0; m < 4; ++m)
; #pragma unroll
;                     for (int n = 0; n < 2; ++n) { acc[a][b][m][n] = (f32x4){0.f, 0.f, 0.f, 0.f}; if constexpr (FP8) asm volatile("" : "+v"(acc[a][b][m][n])); }
;         cur = nxt; cA = nA; cB = nB; ++ui;
;     __device__ __forceinline__ void operator()(const f32x4 (&acc)[2][2][4][2], const Unit& u, int wr, int wc, int fr, int fq) const {
;     ...
;             for (int m = 0; m < 4; ++m) { const size_t r = (size_t)(row0 + ai * HALF + m * 16); float ss = 0.f;
; #pragma unroll
;                 for (int bj = 0; bj < 2; ++bj) { const size_t off = r * DM + col0 + bj * HALF;
;                     const f32x4 v0 = acc[ai][bj][m][0] * ascale + xv[m][bj][0], v1 = acc[ai][bj][m][1] * ascale + xv[m][bj][1];
;                     if (!WB) { *(f32x4*)(out + off) = v0; *(f32x4*)(out + off + 4) = v1; }
;                     if (WB) { u32x4 w; w.x = cvt_pk_bf16(v0[0], v0[1]); w.y = cvt_pk_bf16(v0[2], v0[3]); w.z = cvt_pk_bf16(v1[0], v1[1]); w.w = cvt_pk_bf16(v1[2], v1[3]); *(u32x4*)(xb + off) = w; }
;                     ss += (v0[0] * v0[0] + v0[1] * v0[1]) + (v0[2] * v0[2] + v0[3] * v0[3]) + (v1[0] * v1[0] + v1[1] * v1[1]) + (v1[2] * v1[2] + v1[3] * v1[3]); }
;                 ss += __shfl_xor(ss, 16); ss += __shfl_xor(ss, 32);
;                 if (fq == 0) ssq[r * 16 + u.pn * 4 + wc] = ss; }
	v_add_f32_e32 v128, v128, v129
	ds_bpermute_b32 v129, v206, v128
	s_waitcnt lgkmcnt(0)
	v_add_f32_e32 v128, v128, v129
	s_and_saveexec_b64 s[50:51], vcc
	global_store_dword v[226:227], v128, off
	s_or_b64 exec, exec, s[50:51]
	v_lshl_add_u64 v[224:225], v[224:225], 0, s[82:83]
	v_lshl_add_u64 v[226:227], v[226:227], 0, s[86:87]
	s_waitcnt vmcnt(15)
	v_pk_fma_f32 v[12:13], v[12:13], s[40:41], v[144:145] op_sel_hi:[1,0,1]
	v_pk_fma_f32 v[14:15], v[14:15], s[40:41], v[146:147] op_sel_hi:[1,0,1]
	v_pk_fma_f32 v[4:5], v[4:5], s[40:41], v[148:149] op_sel_hi:[1,0,1]
	v_pk_fma_f32 v[6:7], v[6:7], s[40:41], v[150:151] op_sel_hi:[1,0,1]
	v_pk_fma_f32 v[8:9], v[8:9], s[40:41], v[152:153] op_sel_hi:[1,0,1]
	v_pk_fma_f32 v[10:11], v[10:11], s[40:41], v[154:155] op_sel_hi:[1,0,1]
	v_pk_fma_f32 v[0:1], v[0:1], s[40:41], v[156:157] op_sel_hi:[1,0,1]
	v_pk_fma_f32 v[2:3], v[2:3], s[40:41], v[158:159] op_sel_hi:[1,0,1]
	v_mul_f32_e32 v144, v13, v13
	v_mul_f32_e32 v145, v15, v15
	v_mul_f32_e32 v146, v5, v5
	v_mul_f32_e32 v147, v7, v7
	v_mul_f32_e32 v148, v9, v9
	v_mul_f32_e32 v149, v11, v11
	v_mul_f32_e32 v150, v1, v1
	v_mul_f32_e32 v151, v3, v3
	v_fmac_f32_e32 v144, v12, v12
	v_fmac_f32_e32 v145, v14, v14
	v_fmac_f32_e32 v146, v4, v4
	v_fmac_f32_e32 v147, v6, v6
	v_fmac_f32_e32 v148, v8, v8
	v_fmac_f32_e32 v149, v10, v10
	v_fmac_f32_e32 v150, v0, v0
	v_fmac_f32_e32 v151, v2, v2
	v_cvt_pk_bf16_f32 v152, v12, v13
	v_cvt_pk_bf16_f32 v153, v14, v15
	v_cvt_pk_bf16_f32 v154, v4, v5
	v_cvt_pk_bf16_f32 v155, v6, v7
	v_cvt_pk_bf16_f32 v156, v8, v9
	v_cvt_pk_bf16_f32 v157, v10, v11
	v_cvt_pk_bf16_f32 v158, v0, v1
	v_cvt_pk_bf16_f32 v159, v2, v3
	global_store_dwordx4 v[224:225], v[152:155], off
	global_store_dwordx4 v[224:225], v[156:159], off offset:256
	v_add_f32_e32 v144, v144, v145
	v_add_f32_e32 v146, v146, v147
	v_add_f32_e32 v148, v148, v149
	v_add_f32_e32 v150, v150, v151
	v_add_f32_e32 v144, v144, v146
	v_add_f32_e32 v148, v148, v150
	v_add_f32_e32 v144, v144, v148
	ds_bpermute_b32 v145, v205, v144
	s_waitcnt lgkmcnt(0)
	v_add_f32_e32 v144, v144, v145
	ds_bpermute_b32 v145, v206, v144
	s_waitcnt lgkmcnt(0)
	v_add_f32_e32 v144, v144, v145
	s_and_saveexec_b64 s[50:51], vcc
	global_store_dword v[226:227], v144, off
	s_or_b64 exec, exec, s[50:51]
	s_andn2_b64 vcc, exec, s[4:5]
	s_mov_b64 s[4:5], -1
	s_cbranch_vccnz .LBB0_338
	s_mov_b32 s9, s8
	s_mov_b32 s10, s8
	s_mov_b32 s11, s8
	s_waitcnt lgkmcnt(0)
	v_mov_b64_e32 v[0:1], s[8:9]
	v_mov_b64_e32 v[118:119], s[10:11]
	v_mov_b64_e32 v[114:115], s[10:11]
	v_mov_b64_e32 v[110:111], s[10:11]
	v_mov_b64_e32 v[102:103], s[10:11]
	v_mov_b64_e32 v[94:95], s[10:11]
	v_mov_b64_e32 v[86:87], s[10:11]
	v_mov_b64_e32 v[78:79], s[10:11]
	v_mov_b64_e32 v[70:71], s[10:11]
	v_mov_b64_e32 v[126:127], s[10:11]
	v_mov_b64_e32 v[122:123], s[10:11]
	v_mov_b64_e32 v[106:107], s[10:11]
	v_mov_b64_e32 v[98:99], s[10:11]
	v_mov_b64_e32 v[90:91], s[10:11]
	v_mov_b64_e32 v[82:83], s[10:11]
	v_mov_b64_e32 v[74:75], s[10:11]
	v_mov_b64_e32 v[66:67], s[10:11]
	v_mov_b64_e32 v[54:55], s[10:11]
	v_mov_b64_e32 v[50:51], s[10:11]
	v_mov_b64_e32 v[46:47], s[10:11]
	v_mov_b64_e32 v[38:39], s[10:11]
	v_mov_b64_e32 v[30:31], s[10:11]
	v_mov_b64_e32 v[22:23], s[10:11]
	v_mov_b64_e32 v[14:15], s[10:11]
	v_mov_b64_e32 v[4:5], s[8:9]
	v_mov_b64_e32 v[62:63], s[10:11]
	v_mov_b64_e32 v[58:59], s[10:11]
	v_mov_b64_e32 v[42:43], s[10:11]
	v_mov_b64_e32 v[34:35], s[10:11]
	v_mov_b64_e32 v[26:27], s[10:11]
	v_mov_b64_e32 v[18:19], s[10:11]
	v_mov_b64_e32 v[8:9], s[8:9]
	v_mov_b64_e32 v[2:3], s[10:11]
	v_mov_b64_e32 v[116:117], s[8:9]
	v_mov_b64_e32 v[112:113], s[8:9]
	v_mov_b64_e32 v[108:109], s[8:9]
	v_mov_b64_e32 v[100:101], s[8:9]
	v_mov_b64_e32 v[92:93], s[8:9]
	v_mov_b64_e32 v[84:85], s[8:9]
	v_mov_b64_e32 v[76:77], s[8:9]
	v_mov_b64_e32 v[68:69], s[8:9]
	v_mov_b64_e32 v[124:125], s[8:9]
	v_mov_b64_e32 v[120:121], s[8:9]
	v_mov_b64_e32 v[104:105], s[8:9]
	v_mov_b64_e32 v[96:97], s[8:9]
	v_mov_b64_e32 v[88:89], s[8:9]
	v_mov_b64_e32 v[80:81], s[8:9]
	v_mov_b64_e32 v[72:73], s[8:9]
	v_mov_b64_e32 v[64:65], s[8:9]
	v_mov_b64_e32 v[52:53], s[8:9]
	v_mov_b64_e32 v[48:49], s[8:9]
	v_mov_b64_e32 v[44:45], s[8:9]
	v_mov_b64_e32 v[36:37], s[8:9]
	v_mov_b64_e32 v[28:29], s[8:9]
	v_mov_b64_e32 v[20:21], s[8:9]
	v_mov_b64_e32 v[12:13], s[8:9]
	v_mov_b64_e32 v[6:7], s[10:11]
	v_mov_b64_e32 v[60:61], s[8:9]
	v_mov_b64_e32 v[56:57], s[8:9]
	v_mov_b64_e32 v[40:41], s[8:9]
	v_mov_b64_e32 v[32:33], s[8:9]
	v_mov_b64_e32 v[24:25], s[8:9]
	v_mov_b64_e32 v[16:17], s[8:9]
	v_mov_b64_e32 v[10:11], s[10:11]
	s_andn2_b64 vcc, exec, s[6:7]
	s_cbranch_vccnz .LBB0_337
	s_mov_b32 s100, 1
	s_branch .LBB0_337

; #define PG8_BAR __builtin_amdgcn_s_barrier()
; template <class Epi, class Sched, bool ALIGN_EPI = false, bool SP2 = false, bool FP8 = false>
; __device__ __forceinline__ void gemm_phase(PG8_LAS unsigned char* lds, const Gemm g, const Sched& S, const Epi& E) {
;     ...
;         if constexpr (ALIGN_EPI) { if (wr == 0) PG8_BAR; }
;     __device__ __forceinline__ void operator()(f32x4 (&acc)[2][2][4][2], const Unit& u, int wr, int wc, int fr, int fq) const {
;         const int row0 = u.pm * BM + wr * 64 + fr, col0 = u.pn * BM + wc * 32 + 8 * fq;
; #pragma unroll
;         for (int ai = 0; ai < 2; ++ai) {
;             u32x4 xv[4][2];
; #pragma unroll
;             for (int m = 0; m < 4; ++m)
; #pragma unroll
;                 for (int bj = 0; bj < 2; ++bj) { const size_t off = (size_t)(row0 + ai * HALF + m * 16) * DM + col0 + bj * HALF; xv[m][bj] = *(const u32x4*)(xb + off); }
; #pragma unroll
;             for (int m = 0; m < 4; ++m) { const size_t r = (size_t)(row0 + ai * HALF + m * 16); float ss = 0.f;
; #pragma unroll
;                 for (int bj = 0; bj < 2; ++bj) { const u32x4 xw = xv[m][bj];
;                     const f32x4 x0 = {bf_lo(xw.x), bf_hi(xw.x), bf_lo(xw.y), bf_hi(xw.y)}, x1 = {bf_lo(xw.z), bf_hi(xw.z), bf_lo(xw.w), bf_hi(xw.w)};
;                     const f32x4 v0 = acc[ai][bj][m][0] + x0, v1 = acc[ai][bj][m][1] + x1; acc[ai][bj][m][0] = v0; acc[ai][bj][m][1] = v1;
;                     ss += (v0[0] * v0[0] + v0[1] * v0[1]) + (v0[2] * v0[2] + v0[3] * v0[3]) + (v1[0] * v1[0] + v1[1] * v1[1]) + (v1[2] * v1[2] + v1[3] * v1[3]); }
;                 ss += __shfl_xor(ss, 16); ss += __shfl_xor(ss, 32);
;                 if (fq == 0) __hip_atomic_store(ssq + r * 16 + u.pn * 4 + wc, ss, __ATOMIC_RELAXED, __HIP_MEMORY_SCOPE_AGENT); }
.LBB0_430:
	v_lshl_add_u32 v176, s38, 8, v198
	v_lshl_or_b32 v178, s6, 8, v200
	v_ashrrev_i32_e32 v179, 31, v178
	v_ashrrev_i32_e32 v177, 31, v176
	v_lshl_add_u64 v[196:197], v[178:179], 1, s[16:17]
	v_lshlrev_b64 v[128:129], 11, v[176:177]
	v_lshl_add_u64 v[128:129], v[196:197], 0, v[128:129]
	global_load_dwordx4 v[180:183], v[128:129], off
	global_load_dwordx4 v[184:187], v[128:129], off offset:256
	v_or_b32_e32 v174, 16, v176
	v_or_b32_e32 v172, 32, v176
	v_or_b32_e32 v170, 48, v176
	v_ashrrev_i32_e32 v175, 31, v174
	v_ashrrev_i32_e32 v173, 31, v172
	v_ashrrev_i32_e32 v171, 31, v170
	v_lshlrev_b64 v[128:129], 11, v[174:175]
	v_lshlrev_b64 v[130:131], 11, v[172:173]
	v_lshlrev_b64 v[132:133], 11, v[170:171]
	v_lshl_add_u64 v[128:129], v[196:197], 0, v[128:129]
	v_lshl_add_u64 v[130:131], v[196:197], 0, v[130:131]
	v_lshl_add_u64 v[188:189], v[196:197], 0, v[132:133]
	global_load_dwordx4 v[148:151], v[128:129], off
	global_load_dwordx4 v[144:147], v[128:129], off offset:256
	global_load_dwordx4 v[140:143], v[130:131], off
	global_load_dwordx4 v[136:139], v[130:131], off offset:256
	global_load_dwordx4 v[132:135], v[188:189], off
	s_nop 0
	global_load_dwordx4 v[128:131], v[188:189], off offset:256
	v_lshlrev_b64 v[254:255], 11, v[176:177]
	v_lshl_add_u64 v[254:255], v[196:197], 0, v[254:255]
	s_mov_b64 s[60:61], 0x40000
	v_lshl_add_u64 v[254:255], v[254:255], 0, s[60:61]
	global_load_dwordx4 v[222:225], v[254:255], off
	global_load_dwordx4 v[226:229], v[254:255], off offset:256
	s_mov_b64 s[60:61], 0x8000
	v_lshl_add_u64 v[254:255], v[254:255], 0, s[60:61]
	global_load_dwordx4 v[230:233], v[254:255], off
	global_load_dwordx4 v[234:237], v[254:255], off offset:256
	v_lshl_add_u64 v[254:255], v[254:255], 0, s[60:61]
	global_load_dwordx4 v[238:241], v[254:255], off
	global_load_dwordx4 v[242:245], v[254:255], off offset:256
	v_lshl_add_u64 v[254:255], v[254:255], 0, s[60:61]
	global_load_dwordx4 v[246:249], v[254:255], off
	global_load_dwordx4 v[250:253], v[254:255], off offset:256
	s_and_b64 vcc, exec, s[14:15]
	s_cbranch_vccz .Lmy_ab_p6
	s_barrier
.Lmy_ab_p6:
	v_and_b32_e32 v189, 64, v204
	v_xor_b32_e32 v188, 16, v204
	v_add_u32_e32 v207, 64, v189
	v_cmp_lt_i32_e32 vcc, v188, v207
	s_lshl_b32 s40, s6, 2
	s_ashr_i32 s41, s40, 31
	v_cndmask_b32_e32 v188, v204, v188, vcc
	v_lshlrev_b32_e32 v206, 2, v188
	s_waitcnt vmcnt(8)
	v_lshlrev_b32_e32 v188, 16, v180
	v_and_b32_e32 v189, 0xffff0000, v180
	v_lshlrev_b32_e32 v180, 16, v181
	v_and_b32_e32 v181, 0xffff0000, v181
	v_lshlrev_b32_e32 v192, 16, v184
	v_and_b32_e32 v193, 0xffff0000, v184
	v_lshlrev_b32_e32 v184, 16, v185
	v_and_b32_e32 v185, 0xffff0000, v185
	v_lshlrev_b32_e32 v190, 16, v182
	v_and_b32_e32 v191, 0xffff0000, v182
	v_lshlrev_b32_e32 v194, 16, v186
	v_and_b32_e32 v195, 0xffff0000, v186
	v_pk_add_f32 v[126:127], v[126:127], v[180:181]
	v_pk_add_f32 v[124:125], v[124:125], v[188:189]
	v_pk_add_f32 v[118:119], v[118:119], v[184:185]
	v_pk_add_f32 v[116:117], v[116:117], v[192:193]
	v_lshlrev_b32_e32 v182, 16, v183
	v_and_b32_e32 v183, 0xffff0000, v183
	v_lshlrev_b32_e32 v186, 16, v187
	v_and_b32_e32 v187, 0xffff0000, v187
	v_pk_add_f32 v[120:121], v[120:121], v[190:191]
	v_pk_add_f32 v[112:113], v[112:113], v[194:195]
	v_mul_f32_e32 v180, v125, v125
	v_mul_f32_e32 v181, v127, v127
	v_mul_f32_e32 v184, v117, v117
	v_mul_f32_e32 v185, v119, v119
	v_pk_add_f32 v[122:123], v[122:123], v[182:183]
	v_pk_add_f32 v[114:115], v[114:115], v[186:187]
	v_mul_f32_e32 v182, v121, v121
	v_mul_f32_e32 v186, v113, v113
	v_fmac_f32_e32 v180, v124, v124
	v_fmac_f32_e32 v181, v126, v126
	v_fmac_f32_e32 v184, v116, v116
	v_fmac_f32_e32 v185, v118, v118
	v_mul_f32_e32 v183, v123, v123
	v_mul_f32_e32 v187, v115, v115
	v_fmac_f32_e32 v182, v120, v120
	v_fmac_f32_e32 v186, v112, v112
	v_add_f32_e32 v180, v180, v181
	v_add_f32_e32 v181, v184, v185
	v_fmac_f32_e32 v183, v122, v122
	v_fmac_f32_e32 v187, v114, v114
	v_add_f32_e32 v180, v182, v180
	v_add_f32_e32 v181, v186, v181
	v_add_f32_e32 v180, v183, v180
	v_add_f32_e32 v181, v187, v181
	v_add_f32_e32 v180, v180, v181
	ds_bpermute_b32 v181, v206, v180
	v_xor_b32_e32 v182, 32, v204
	v_cmp_lt_i32_e32 vcc, v182, v207
	v_lshlrev_b64 v[188:189], 6, v[176:177]
	s_waitcnt lgkmcnt(0)
	v_add_f32_e32 v180, v180, v181
	v_cndmask_b32_e32 v182, v204, v182, vcc
	v_lshlrev_b32_e32 v207, 2, v182
	ds_bpermute_b32 v181, v207, v180
	s_and_saveexec_b64 s[42:43], s[0:1]
	s_cbranch_execz .LBB0_432
	s_waitcnt lgkmcnt(0)
	v_add_f32_e32 v182, v180, v181
	v_lshl_add_u64 v[180:181], s[10:11], 0, v[188:189]
	v_lshl_add_u64 v[180:181], s[40:41], 2, v[180:181]
	s_lshl_b32 s6, s53, 2
	v_lshl_add_u64 v[180:181], v[180:181], 0, s[6:7]
	global_store_dword v[180:181], v182, off sc1
